# GEMM loops: first K-iteration peeled with srcC=0 MFMAs, so the 128 v_mov accumulator zero-inits per tile are gone (all four GEMM instances)
# speedup vs baseline: 1.0056x; 1.0056x over previous
; #define PG8_STAGE(bufoff, gbase, voff) do { _Pragma("unroll") for (int _i = 0; _i < 2; ++_i) \
;         __builtin_amdgcn_global_load_lds((const unsigned*)((const char*)(gbase) + (voff)[_i]), (PG8_LAS unsigned*)(lds + (bufoff) + ldsw + _i * 8192), 16, 0, 0); } while (0)
; #define PG8_LDA(dst, b, h) do { _Pragma("unroll") for (int m = 0; m < 4; ++m) _Pragma("unroll") for (int k = 0; k < 2; ++k) dst[m][k] = *(const PG8_LAS bf16x8*)(lds + PG8_SA(b, h) + aoff + m * 2048 + k * 1024); } while (0)
; #define PG8_LDB(dst, b, h) do { _Pragma("unroll") for (int n = 0; n < 2; ++n) _Pragma("unroll") for (int k = 0; k < 2; ++k) dst[n][k] = *(const PG8_LAS bf16x8*)(lds + PG8_SB(b, h) + boff + n * 2048 + k * 1024); } while (0)
; #define PG8_WAIT_V(n) asm volatile("s_waitcnt vmcnt(" #n ")" ::: "memory")
; #define PG8_WAIT_L(n) asm volatile("s_waitcnt lgkmcnt(" #n ")" ::: "memory")
; #define PG8_BAR __builtin_amdgcn_s_barrier()
; template <class Epi, class Sched, bool ALIGN_EPI = false, bool SP2 = false>
; __device__ __forceinline__ void gemm_phase(PG8_LAS unsigned char* lds, const Gemm g, const Sched& S, const Epi& E) {
;     ...
;     f32x4 acc[2][2][4][2];
; #pragma unroll
;     for (int a = 0; a < 2; ++a)
; #pragma unroll
;         for (int b = 0; b < 2; ++b)
; #pragma unroll
;             for (int m = 0; m < 4; ++m)
; #pragma unroll
;                 for (int n = 0; n < 2; ++n) acc[a][b][m][n] = (f32x4){0.f, 0.f, 0.f, 0.f};
;     ...
;         for (int t = 0; t < nt; t += 2) {
;             const bool last = (t == nt - 2);
;             const char* a1 = cA + (size_t)(t + 1) * kstep;
;             const char* a2 = last ? nA : cA + (size_t)(t + 2) * kstep; const char* b2 = last ? nB : cB + (size_t)(t + 2) * kstep;
;             const char* a3 = a2 + kstep; const char* b3 = b2 + kstep;
;             if (last && has_next) S.a_ready(nxt);
;             if constexpr (SP2) {
;             PG8_LDB(B0, 0, 0); PG8_LDB(B1, 0, 1); PG8_SCHED; PG8_LDA(At, 0, 0); PG8_STAGE(PG8_SA(1, 1), a1 + hstep, voffA);
;             PG8_WAIT_V(8); PG8_WAIT_L(0); PG8_BAR; PG8_MMA(0, 0, At, B0); PG8_MMA(0, 1, At, B1); PG8_BAR; PG8_SCHED;
;             PG8_LDA(At, 0, 1); PG8_STAGE(PG8_SB(0, 0), b2, voffB); PG8_STAGE(PG8_SB(0, 1), b2 + hstep, voffB); PG8_STAGE(PG8_SA(0, 0), a2, voffA);
;             PG8_WAIT_V(8); PG8_WAIT_L(0); PG8_BAR; PG8_MMA(1, 0, At, B0); PG8_MMA(1, 1, At, B1); PG8_BAR; PG8_SCHED;
.LBB0_37:
	s_add_u32 s31, s4, 0x100
	s_addc_u32 s41, s5, 0
	s_mov_b32 s43, -2
	s_add_u32 s38, s36, 0x100
	s_addc_u32 s39, s37, 0
	s_add_i32 s47, 0, 0x10000
	s_cmp_eq_u32 s43, 28
	s_cselect_b32 s65, s9, s39
	s_cselect_b32 s64, s8, s38
	s_cselect_b32 s5, s19, s41
	s_cselect_b32 s4, s18, s31
	s_add_i32 s50, 0, 0x14000
	v_add_u32_e32 v156, s47, v1
	v_add_u32_e32 v172, s50, v1
	ds_read_b128 v[144:147], v156
	ds_read_b128 v[148:151], v156 offset:1024
	ds_read_b128 v[152:155], v156 offset:2048
	ds_read_b128 v[156:159], v156 offset:3072
	ds_read_b128 v[160:163], v172
	ds_read_b128 v[164:167], v172 offset:1024
	ds_read_b128 v[168:171], v172 offset:2048
	ds_read_b128 v[172:175], v172 offset:3072
	v_lshl_add_u64 v[208:209], s[36:37], 0, v[142:143]
	s_add_i32 m0, s54, 0xc000
	ds_read_b128 v[176:179], v17
	ds_read_b128 v[180:183], v17 offset:1024
	ds_read_b128 v[184:187], v17 offset:2048
	ds_read_b128 v[188:191], v17 offset:3072
	ds_read_b128 v[192:195], v17 offset:4096
	ds_read_b128 v[196:199], v17 offset:5120
	ds_read_b128 v[200:203], v17 offset:6144
	ds_read_b128 v[204:207], v17 offset:7168
	global_load_lds_dwordx4 v[208:209], off
	v_lshl_add_u64 v[208:209], s[36:37], 0, v[140:141]
	s_add_i32 m0, s54, 0xe000
	s_nop 0
	global_load_lds_dwordx4 v[208:209], off
	s_waitcnt vmcnt(8)
	s_waitcnt lgkmcnt(0)
	s_barrier
	s_setprio 1
	s_waitcnt lgkmcnt(0)
	v_mfma_f32_16x16x32_bf16 v[130:133], v[144:147], v[176:179], 0
	v_mfma_f32_16x16x32_bf16 v[126:129], v[152:155], v[176:179], 0
	v_mfma_f32_16x16x32_bf16 v[114:117], v[144:147], v[184:187], 0
	v_mfma_f32_16x16x32_bf16 v[110:113], v[152:155], v[184:187], 0
	v_mfma_f32_16x16x32_bf16 v[98:101], v[144:147], v[192:195], 0
	v_mfma_f32_16x16x32_bf16 v[94:97], v[152:155], v[192:195], 0
	v_mfma_f32_16x16x32_bf16 v[82:85], v[144:147], v[200:203], 0
	v_mfma_f32_16x16x32_bf16 v[78:81], v[152:155], v[200:203], 0
	v_mfma_f32_16x16x32_bf16 v[130:133], v[148:151], v[180:183], v[130:133]
	v_mfma_f32_16x16x32_bf16 v[126:129], v[156:159], v[180:183], v[126:129]
	v_mfma_f32_16x16x32_bf16 v[114:117], v[148:151], v[188:191], v[114:117]
	v_mfma_f32_16x16x32_bf16 v[110:113], v[156:159], v[188:191], v[110:113]
	v_mfma_f32_16x16x32_bf16 v[98:101], v[148:151], v[196:199], v[98:101]
	v_mfma_f32_16x16x32_bf16 v[94:97], v[156:159], v[196:199], v[94:97]
	v_mfma_f32_16x16x32_bf16 v[82:85], v[148:151], v[204:207], v[82:85]
	v_mfma_f32_16x16x32_bf16 v[78:81], v[156:159], v[204:207], v[78:81]
	s_setprio 0
	s_setprio 1
	v_mfma_f32_16x16x32_bf16 v[122:125], v[160:163], v[176:179], 0
	v_mfma_f32_16x16x32_bf16 v[118:121], v[168:171], v[176:179], 0
	v_mfma_f32_16x16x32_bf16 v[106:109], v[160:163], v[184:187], 0
	v_mfma_f32_16x16x32_bf16 v[102:105], v[168:171], v[184:187], 0
	v_mfma_f32_16x16x32_bf16 v[90:93], v[160:163], v[192:195], 0
	v_mfma_f32_16x16x32_bf16 v[86:89], v[168:171], v[192:195], 0
	v_mfma_f32_16x16x32_bf16 v[74:77], v[160:163], v[200:203], 0
	v_mfma_f32_16x16x32_bf16 v[70:73], v[168:171], v[200:203], 0
	v_mfma_f32_16x16x32_bf16 v[122:125], v[164:167], v[180:183], v[122:125]
	v_mfma_f32_16x16x32_bf16 v[118:121], v[172:175], v[180:183], v[118:121]
	v_mfma_f32_16x16x32_bf16 v[106:109], v[164:167], v[188:191], v[106:109]
	v_mfma_f32_16x16x32_bf16 v[102:105], v[172:175], v[188:191], v[102:105]
	v_mfma_f32_16x16x32_bf16 v[90:93], v[164:167], v[196:199], v[90:93]
	v_mfma_f32_16x16x32_bf16 v[86:89], v[172:175], v[196:199], v[86:89]
	v_mfma_f32_16x16x32_bf16 v[74:77], v[164:167], v[204:207], v[74:77]
	v_mfma_f32_16x16x32_bf16 v[70:73], v[172:175], v[204:207], v[70:73]
	s_setprio 0
	s_barrier
	s_add_i32 s36, s47, s46
	v_lshl_add_u64 v[208:209], s[4:5], 0, v[136:137]
	s_mov_b32 m0, s36
	ds_read_b128 v[176:179], v17 offset:16384
	ds_read_b128 v[180:183], v17 offset:17408
	ds_read_b128 v[184:187], v17 offset:18432
	ds_read_b128 v[188:191], v17 offset:19456
	ds_read_b128 v[192:195], v17 offset:20480
	ds_read_b128 v[196:199], v17 offset:21504
	ds_read_b128 v[200:203], v17 offset:22528
	ds_read_b128 v[204:207], v17 offset:23552
	global_load_lds_dwordx4 v[208:209], off
	s_add_i32 m0, s36, 0x2000
	s_add_u32 s36, s4, 0x84000
	v_lshl_add_u64 v[214:215], s[4:5], 0, v[14:15]
	s_addc_u32 s37, s5, 0
	s_add_i32 s47, s50, s46
	global_load_lds_dwordx4 v[214:215], off
	v_lshl_add_u64 v[216:217], s[36:37], 0, v[136:137]
	s_mov_b32 m0, s47
	v_lshl_add_u64 v[220:221], s[64:65], 0, v[134:135]
	global_load_lds_dwordx4 v[216:217], off
	v_lshl_add_u64 v[216:217], s[36:37], 0, v[14:15]
	s_add_i32 m0, s47, 0x2000
	s_nop 0
	global_load_lds_dwordx4 v[216:217], off
	v_lshl_add_u64 v[216:217], s[64:65], 0, v[138:139]
	s_mov_b32 m0, s54
	s_nop 0
	global_load_lds_dwordx4 v[216:217], off
	s_mov_b32 m0, s68
	s_nop 0
	global_load_lds_dwordx4 v[220:221], off
	s_waitcnt vmcnt(8)
	s_waitcnt lgkmcnt(0)
	s_barrier
; #define PG8_STAGE(bufoff, gbase, voff) do { _Pragma("unroll") for (int _i = 0; _i < 2; ++_i) \
;         __builtin_amdgcn_global_load_lds((const unsigned*)((const char*)(gbase) + (voff)[_i]), (PG8_LAS unsigned*)(lds + (bufoff) + ldsw + _i * 8192), 16, 0, 0); } while (0)
; #define PG8_LDA(dst, b, h) do { _Pragma("unroll") for (int m = 0; m < 4; ++m) _Pragma("unroll") for (int k = 0; k < 2; ++k) dst[m][k] = *(const PG8_LAS bf16x8*)(lds + PG8_SA(b, h) + aoff + m * 2048 + k * 1024); } while (0)
; #define PG8_LDB(dst, b, h) do { _Pragma("unroll") for (int n = 0; n < 2; ++n) _Pragma("unroll") for (int k = 0; k < 2; ++k) dst[n][k] = *(const PG8_LAS bf16x8*)(lds + PG8_SB(b, h) + boff + n * 2048 + k * 1024); } while (0)
; #define PG8_MMA(ai, bj, At, Bt) do { __builtin_amdgcn_s_setprio(1); _Pragma("unroll") for (int m = 0; m < 4; ++m) _Pragma("unroll") for (int n = 0; n < 2; ++n) _Pragma("unroll") for (int k = 0; k < 2; ++k) \
;         acc[ai][bj][m][n] = __builtin_amdgcn_mfma_f32_16x16x32_bf16(Bt[n][k], At[m][k], acc[ai][bj][m][n], 0, 0, 0); __builtin_amdgcn_s_setprio(0); } while (0)
; #define PG8_WAIT_V(n) asm volatile("s_waitcnt vmcnt(" #n ")" ::: "memory")
; #define PG8_WAIT_L(n) asm volatile("s_waitcnt lgkmcnt(" #n ")" ::: "memory")
; #define PG8_BAR __builtin_amdgcn_s_barrier()
; #define PG8_SCHED __builtin_amdgcn_sched_barrier(0)
; template <class Epi, class Sched, bool ALIGN_EPI = false, bool SP2 = false>
; __device__ __forceinline__ void gemm_phase(PG8_LAS unsigned char* lds, const Gemm g, const Sched& S, const Epi& E) {
;     ...
;             PG8_WAIT_V(8); PG8_WAIT_L(0); PG8_BAR; PG8_MMA(1, 0, At, B0); PG8_MMA(1, 1, At, B1); PG8_BAR; PG8_SCHED;
;             PG8_LDB(B0, 1, 0); PG8_LDB(B1, 1, 1); PG8_SCHED; PG8_LDA(At, 1, 0); PG8_STAGE(PG8_SA(0, 1), a2 + hstep, voffA);
;             PG8_WAIT_V(8); PG8_WAIT_L(0); PG8_BAR; PG8_MMA(0, 0, At, B0); PG8_MMA(0, 1, At, B1); PG8_BAR; PG8_SCHED;
	s_setprio 1
	s_waitcnt lgkmcnt(0)
	v_mfma_f32_16x16x32_bf16 v[66:69], v[144:147], v[176:179], 0
	v_mfma_f32_16x16x32_bf16 v[62:65], v[152:155], v[176:179], 0
	v_mfma_f32_16x16x32_bf16 v[50:53], v[144:147], v[184:187], 0
	v_mfma_f32_16x16x32_bf16 v[46:49], v[152:155], v[184:187], 0
	v_mfma_f32_16x16x32_bf16 v[34:37], v[144:147], v[192:195], 0
	v_mfma_f32_16x16x32_bf16 v[30:33], v[152:155], v[192:195], 0
	v_mfma_f32_16x16x32_bf16 v[18:21], v[144:147], v[200:203], 0
	v_mfma_f32_16x16x32_bf16 v[10:13], v[152:155], v[200:203], 0
	v_mfma_f32_16x16x32_bf16 v[66:69], v[148:151], v[180:183], v[66:69]
	v_mfma_f32_16x16x32_bf16 v[62:65], v[156:159], v[180:183], v[62:65]
	v_mfma_f32_16x16x32_bf16 v[50:53], v[148:151], v[188:191], v[50:53]
	v_mfma_f32_16x16x32_bf16 v[46:49], v[156:159], v[188:191], v[46:49]
	v_mfma_f32_16x16x32_bf16 v[34:37], v[148:151], v[196:199], v[34:37]
	v_mfma_f32_16x16x32_bf16 v[30:33], v[156:159], v[196:199], v[30:33]
	v_mfma_f32_16x16x32_bf16 v[18:21], v[148:151], v[204:207], v[18:21]
	v_mfma_f32_16x16x32_bf16 v[10:13], v[156:159], v[204:207], v[10:13]
	s_setprio 0
	s_setprio 1
	v_mfma_f32_16x16x32_bf16 v[58:61], v[160:163], v[176:179], 0
	v_mfma_f32_16x16x32_bf16 v[54:57], v[168:171], v[176:179], 0
	v_mfma_f32_16x16x32_bf16 v[42:45], v[160:163], v[184:187], 0
	v_mfma_f32_16x16x32_bf16 v[38:41], v[168:171], v[184:187], 0
	v_mfma_f32_16x16x32_bf16 v[26:29], v[160:163], v[192:195], 0
	v_mfma_f32_16x16x32_bf16 v[22:25], v[168:171], v[192:195], 0
	v_mfma_f32_16x16x32_bf16 v[6:9], v[160:163], v[200:203], 0
	v_mfma_f32_16x16x32_bf16 v[2:5], v[168:171], v[200:203], 0
	v_mfma_f32_16x16x32_bf16 v[58:61], v[164:167], v[180:183], v[58:61]
	v_mfma_f32_16x16x32_bf16 v[54:57], v[172:175], v[180:183], v[54:57]
	v_mfma_f32_16x16x32_bf16 v[42:45], v[164:167], v[188:191], v[42:45]
	v_mfma_f32_16x16x32_bf16 v[38:41], v[172:175], v[188:191], v[38:41]
	v_mfma_f32_16x16x32_bf16 v[26:29], v[164:167], v[196:199], v[26:29]
	v_mfma_f32_16x16x32_bf16 v[22:25], v[172:175], v[196:199], v[22:25]
	v_mfma_f32_16x16x32_bf16 v[6:9], v[164:167], v[204:207], v[6:9]
	v_mfma_f32_16x16x32_bf16 v[2:5], v[172:175], v[204:207], v[2:5]
	s_setprio 0
	s_barrier
	s_add_i32 s47, 0, 0x18000
	s_add_i32 s50, 0, 0x1c000
	v_add_u32_e32 v156, s47, v1
	v_add_u32_e32 v172, s50, v1
	ds_read_b128 v[144:147], v156
	ds_read_b128 v[148:151], v156 offset:1024
	ds_read_b128 v[152:155], v156 offset:2048
	ds_read_b128 v[156:159], v156 offset:3072
	ds_read_b128 v[160:163], v172
	ds_read_b128 v[164:167], v172 offset:1024
	ds_read_b128 v[168:171], v172 offset:2048
	ds_read_b128 v[172:175], v172 offset:3072
	s_add_u32 s36, s64, 0x84000
	s_addc_u32 s37, s65, 0
	s_mov_b32 m0, s77
	v_lshl_add_u64 v[222:223], s[36:37], 0, v[138:139]
	ds_read_b128 v[176:179], v17 offset:32768
	ds_read_b128 v[180:183], v17 offset:33792
	ds_read_b128 v[184:187], v17 offset:34816
	ds_read_b128 v[188:191], v17 offset:35840
	ds_read_b128 v[192:195], v17 offset:36864
	ds_read_b128 v[196:199], v17 offset:37888
	ds_read_b128 v[200:203], v17 offset:38912
	ds_read_b128 v[204:207], v17 offset:39936
	global_load_lds_dwordx4 v[222:223], off
	v_lshl_add_u64 v[222:223], s[36:37], 0, v[134:135]
	s_mov_b32 m0, s84
	s_nop 0
	global_load_lds_dwordx4 v[222:223], off
	s_waitcnt vmcnt(8)
	s_waitcnt lgkmcnt(0)
	s_barrier
	s_setprio 1
	s_waitcnt lgkmcnt(0)
	v_mfma_f32_16x16x32_bf16 v[130:133], v[144:147], v[176:179], v[130:133]
	v_mfma_f32_16x16x32_bf16 v[126:129], v[152:155], v[176:179], v[126:129]
	v_mfma_f32_16x16x32_bf16 v[114:117], v[144:147], v[184:187], v[114:117]
	v_mfma_f32_16x16x32_bf16 v[110:113], v[152:155], v[184:187], v[110:113]
	v_mfma_f32_16x16x32_bf16 v[98:101], v[144:147], v[192:195], v[98:101]
	v_mfma_f32_16x16x32_bf16 v[94:97], v[152:155], v[192:195], v[94:97]
	v_mfma_f32_16x16x32_bf16 v[82:85], v[144:147], v[200:203], v[82:85]
	v_mfma_f32_16x16x32_bf16 v[78:81], v[152:155], v[200:203], v[78:81]
	v_mfma_f32_16x16x32_bf16 v[130:133], v[148:151], v[180:183], v[130:133]
	v_mfma_f32_16x16x32_bf16 v[126:129], v[156:159], v[180:183], v[126:129]
	v_mfma_f32_16x16x32_bf16 v[114:117], v[148:151], v[188:191], v[114:117]
	v_mfma_f32_16x16x32_bf16 v[110:113], v[156:159], v[188:191], v[110:113]
	v_mfma_f32_16x16x32_bf16 v[98:101], v[148:151], v[196:199], v[98:101]
	v_mfma_f32_16x16x32_bf16 v[94:97], v[156:159], v[196:199], v[94:97]
	v_mfma_f32_16x16x32_bf16 v[82:85], v[148:151], v[204:207], v[82:85]
	v_mfma_f32_16x16x32_bf16 v[78:81], v[156:159], v[204:207], v[78:81]
	s_setprio 0
	s_setprio 1
	v_mfma_f32_16x16x32_bf16 v[122:125], v[160:163], v[176:179], v[122:125]
	v_mfma_f32_16x16x32_bf16 v[118:121], v[168:171], v[176:179], v[118:121]
	v_mfma_f32_16x16x32_bf16 v[106:109], v[160:163], v[184:187], v[106:109]
	v_mfma_f32_16x16x32_bf16 v[102:105], v[168:171], v[184:187], v[102:105]
	v_mfma_f32_16x16x32_bf16 v[90:93], v[160:163], v[192:195], v[90:93]
	v_mfma_f32_16x16x32_bf16 v[86:89], v[168:171], v[192:195], v[86:89]
	v_mfma_f32_16x16x32_bf16 v[74:77], v[160:163], v[200:203], v[74:77]
	v_mfma_f32_16x16x32_bf16 v[70:73], v[168:171], v[200:203], v[70:73]
	v_mfma_f32_16x16x32_bf16 v[122:125], v[164:167], v[180:183], v[122:125]
	v_mfma_f32_16x16x32_bf16 v[118:121], v[172:175], v[180:183], v[118:121]
	v_mfma_f32_16x16x32_bf16 v[106:109], v[164:167], v[188:191], v[106:109]
	v_mfma_f32_16x16x32_bf16 v[102:105], v[172:175], v[188:191], v[102:105]
	v_mfma_f32_16x16x32_bf16 v[90:93], v[164:167], v[196:199], v[90:93]
	v_mfma_f32_16x16x32_bf16 v[86:89], v[172:175], v[196:199], v[86:89]
	v_mfma_f32_16x16x32_bf16 v[74:77], v[164:167], v[204:207], v[74:77]
	v_mfma_f32_16x16x32_bf16 v[70:73], v[172:175], v[204:207], v[70:73]
	s_setprio 0
	s_barrier
; #define PG8_STAGE(bufoff, gbase, voff) do { _Pragma("unroll") for (int _i = 0; _i < 2; ++_i) \
;         __builtin_amdgcn_global_load_lds((const unsigned*)((const char*)(gbase) + (voff)[_i]), (PG8_LAS unsigned*)(lds + (bufoff) + ldsw + _i * 8192), 16, 0, 0); } while (0)
; #define PG8_LDA(dst, b, h) do { _Pragma("unroll") for (int m = 0; m < 4; ++m) _Pragma("unroll") for (int k = 0; k < 2; ++k) dst[m][k] = *(const PG8_LAS bf16x8*)(lds + PG8_SA(b, h) + aoff + m * 2048 + k * 1024); } while (0)
; #define PG8_MMA(ai, bj, At, Bt) do { __builtin_amdgcn_s_setprio(1); _Pragma("unroll") for (int m = 0; m < 4; ++m) _Pragma("unroll") for (int n = 0; n < 2; ++n) _Pragma("unroll") for (int k = 0; k < 2; ++k) \
;         acc[ai][bj][m][n] = __builtin_amdgcn_mfma_f32_16x16x32_bf16(Bt[n][k], At[m][k], acc[ai][bj][m][n], 0, 0, 0); __builtin_amdgcn_s_setprio(0); } while (0)
; #define PG8_WAIT_V(n) asm volatile("s_waitcnt vmcnt(" #n ")" ::: "memory")
; #define PG8_WAIT_L(n) asm volatile("s_waitcnt lgkmcnt(" #n ")" ::: "memory")
; #define PG8_BAR __builtin_amdgcn_s_barrier()
; #define PG8_SCHED __builtin_amdgcn_sched_barrier(0)
; template <class Epi, class Sched, bool ALIGN_EPI = false, bool SP2 = false>
; __device__ __forceinline__ void gemm_phase(PG8_LAS unsigned char* lds, const Gemm g, const Sched& S, const Epi& E) {
;     ...
;             PG8_LDA(At, 1, 1); PG8_STAGE(PG8_SB(1, 0), b3, voffB); PG8_STAGE(PG8_SB(1, 1), b3 + hstep, voffB); PG8_STAGE(PG8_SA(1, 0), a3, voffA);
;             PG8_WAIT_V(8); PG8_WAIT_L(0); PG8_BAR; PG8_MMA(1, 0, At, B0); PG8_MMA(1, 1, At, B1); PG8_BAR; PG8_SCHED;
	s_add_i32 s36, s47, s46
	v_lshl_add_u64 v[208:209], v[208:209], 0, s[48:49]
	s_mov_b32 m0, s36
	ds_read_b128 v[176:179], v17 offset:49152
	ds_read_b128 v[180:183], v17 offset:50176
	ds_read_b128 v[184:187], v17 offset:51200
	ds_read_b128 v[188:191], v17 offset:52224
	ds_read_b128 v[192:195], v17 offset:53248
	ds_read_b128 v[196:199], v17 offset:54272
	ds_read_b128 v[200:203], v17 offset:55296
	ds_read_b128 v[204:207], v17 offset:56320
	global_load_lds_dwordx4 v[208:209], off
	s_add_i32 m0, s36, 0x2000
	s_add_u32 s4, s4, 0x84080
	v_lshl_add_u64 v[208:209], v[214:215], 0, s[48:49]
	s_addc_u32 s5, s5, 0
	s_add_i32 s36, s50, s46
	global_load_lds_dwordx4 v[208:209], off
	v_lshl_add_u64 v[208:209], s[4:5], 0, v[136:137]
	s_mov_b32 m0, s36
	s_nop 0
	global_load_lds_dwordx4 v[208:209], off
	v_lshl_add_u64 v[208:209], s[4:5], 0, v[14:15]
	s_add_i32 m0, s36, 0x2000
	s_nop 0
	global_load_lds_dwordx4 v[208:209], off
	v_lshl_add_u64 v[208:209], v[216:217], 0, s[48:49]
	s_mov_b32 m0, s93
	s_nop 0
	global_load_lds_dwordx4 v[208:209], off
	v_lshl_add_u64 v[208:209], v[220:221], 0, s[48:49]
	s_mov_b32 m0, s94
	s_nop 0
	global_load_lds_dwordx4 v[208:209], off
	s_waitcnt vmcnt(8)
	s_waitcnt lgkmcnt(0)
	s_barrier
	s_setprio 1
	s_waitcnt lgkmcnt(0)
	v_mfma_f32_16x16x32_bf16 v[66:69], v[144:147], v[176:179], v[66:69]
	v_mfma_f32_16x16x32_bf16 v[62:65], v[152:155], v[176:179], v[62:65]
	v_mfma_f32_16x16x32_bf16 v[50:53], v[144:147], v[184:187], v[50:53]
	v_mfma_f32_16x16x32_bf16 v[46:49], v[152:155], v[184:187], v[46:49]
	v_mfma_f32_16x16x32_bf16 v[34:37], v[144:147], v[192:195], v[34:37]
	v_mfma_f32_16x16x32_bf16 v[30:33], v[152:155], v[192:195], v[30:33]
	v_mfma_f32_16x16x32_bf16 v[18:21], v[144:147], v[200:203], v[18:21]
	v_mfma_f32_16x16x32_bf16 v[10:13], v[152:155], v[200:203], v[10:13]
	v_mfma_f32_16x16x32_bf16 v[66:69], v[148:151], v[180:183], v[66:69]
	v_mfma_f32_16x16x32_bf16 v[62:65], v[156:159], v[180:183], v[62:65]
	v_mfma_f32_16x16x32_bf16 v[50:53], v[148:151], v[188:191], v[50:53]
	v_mfma_f32_16x16x32_bf16 v[46:49], v[156:159], v[188:191], v[46:49]
	v_mfma_f32_16x16x32_bf16 v[34:37], v[148:151], v[196:199], v[34:37]
	v_mfma_f32_16x16x32_bf16 v[30:33], v[156:159], v[196:199], v[30:33]
	v_mfma_f32_16x16x32_bf16 v[18:21], v[148:151], v[204:207], v[18:21]
	v_mfma_f32_16x16x32_bf16 v[10:13], v[156:159], v[204:207], v[10:13]
	s_setprio 0
	s_setprio 1
	v_mfma_f32_16x16x32_bf16 v[58:61], v[160:163], v[176:179], v[58:61]
	v_mfma_f32_16x16x32_bf16 v[54:57], v[168:171], v[176:179], v[54:57]
	v_mfma_f32_16x16x32_bf16 v[42:45], v[160:163], v[184:187], v[42:45]
	v_mfma_f32_16x16x32_bf16 v[38:41], v[168:171], v[184:187], v[38:41]
	v_mfma_f32_16x16x32_bf16 v[26:29], v[160:163], v[192:195], v[26:29]
	v_mfma_f32_16x16x32_bf16 v[22:25], v[168:171], v[192:195], v[22:25]
	v_mfma_f32_16x16x32_bf16 v[6:9], v[160:163], v[200:203], v[6:9]
	v_mfma_f32_16x16x32_bf16 v[2:5], v[168:171], v[200:203], v[2:5]
	v_mfma_f32_16x16x32_bf16 v[58:61], v[164:167], v[180:183], v[58:61]
	v_mfma_f32_16x16x32_bf16 v[54:57], v[172:175], v[180:183], v[54:57]
	v_mfma_f32_16x16x32_bf16 v[42:45], v[164:167], v[188:191], v[42:45]
	v_mfma_f32_16x16x32_bf16 v[38:41], v[172:175], v[188:191], v[38:41]
	v_mfma_f32_16x16x32_bf16 v[26:29], v[164:167], v[196:199], v[26:29]
	v_mfma_f32_16x16x32_bf16 v[22:25], v[172:175], v[196:199], v[22:25]
	v_mfma_f32_16x16x32_bf16 v[6:9], v[164:167], v[204:207], v[6:9]
	v_mfma_f32_16x16x32_bf16 v[2:5], v[172:175], v[204:207], v[2:5]
	s_setprio 0
	s_barrier
	s_add_i32 s43, s43, 2
	s_add_u32 s31, s31, 0x100
	s_addc_u32 s41, s41, 0
	s_cmp_gt_u32 s43, 29
	s_mov_b64 s[36:37], s[38:39]
	s_cbranch_scc0 .LBB0_38
	s_branch .Lgemm_exit_a

; #define PG8_BAR __builtin_amdgcn_s_barrier()
; template <class Epi, class Sched, bool ALIGN_EPI = false, bool SP2 = false>
; __device__ __forceinline__ void gemm_phase(PG8_LAS unsigned char* lds, const Gemm g, const Sched& S, const Epi& E) {
;     ...
;         if constexpr (ALIGN_EPI) { if (wr == 0) PG8_BAR; }
.Lgemm_exit_a:
	s_and_b64 vcc, exec, s[16:17]
	s_cbranch_vccz .LBB0_41
	s_barrier

; #define PG8_STAGE(bufoff, gbase, voff) do { _Pragma("unroll") for (int _i = 0; _i < 2; ++_i) \
;         __builtin_amdgcn_global_load_lds((const unsigned*)((const char*)(gbase) + (voff)[_i]), (PG8_LAS unsigned*)(lds + (bufoff) + ldsw + _i * 8192), 16, 0, 0); } while (0)
; #define PG8_LDA(dst, b, h) do { _Pragma("unroll") for (int m = 0; m < 4; ++m) _Pragma("unroll") for (int k = 0; k < 2; ++k) dst[m][k] = *(const PG8_LAS bf16x8*)(lds + PG8_SA(b, h) + aoff + m * 2048 + k * 1024); } while (0)
; #define PG8_LDB(dst, b, h) do { _Pragma("unroll") for (int n = 0; n < 2; ++n) _Pragma("unroll") for (int k = 0; k < 2; ++k) dst[n][k] = *(const PG8_LAS bf16x8*)(lds + PG8_SB(b, h) + boff + n * 2048 + k * 1024); } while (0)
; #define PG8_WAIT_V(n) asm volatile("s_waitcnt vmcnt(" #n ")" ::: "memory")
; #define PG8_WAIT_L(n) asm volatile("s_waitcnt lgkmcnt(" #n ")" ::: "memory")
; #define PG8_BAR __builtin_amdgcn_s_barrier()
; template <class Epi, class Sched, bool ALIGN_EPI = false, bool SP2 = false>
; __device__ __forceinline__ void gemm_phase(PG8_LAS unsigned char* lds, const Gemm g, const Sched& S, const Epi& E) {
;     ...
;     f32x4 acc[2][2][4][2];
; #pragma unroll
;     for (int a = 0; a < 2; ++a)
; #pragma unroll
;         for (int b = 0; b < 2; ++b)
; #pragma unroll
;             for (int m = 0; m < 4; ++m)
; #pragma unroll
;                 for (int n = 0; n < 2; ++n) acc[a][b][m][n] = (f32x4){0.f, 0.f, 0.f, 0.f};
;     ...
;         for (int t = 0; t < nt; t += 2) {
;             const bool last = (t == nt - 2);
;             const char* a1 = cA + (size_t)(t + 1) * kstep;
;             const char* a2 = last ? nA : cA + (size_t)(t + 2) * kstep; const char* b2 = last ? nB : cB + (size_t)(t + 2) * kstep;
;             const char* a3 = a2 + kstep; const char* b3 = b2 + kstep;
;             if (last && has_next) S.a_ready(nxt);
;             if constexpr (SP2) {
;             PG8_LDB(B0, 0, 0); PG8_LDB(B1, 0, 1); PG8_SCHED; PG8_LDA(At, 0, 0); PG8_STAGE(PG8_SA(1, 1), a1 + hstep, voffA);
;             PG8_WAIT_V(8); PG8_WAIT_L(0); PG8_BAR; PG8_MMA(0, 0, At, B0); PG8_MMA(0, 1, At, B1); PG8_BAR; PG8_SCHED;
;             PG8_LDA(At, 0, 1); PG8_STAGE(PG8_SB(0, 0), b2, voffB); PG8_STAGE(PG8_SB(0, 1), b2 + hstep, voffB); PG8_STAGE(PG8_SA(0, 0), a2, voffA);
;             PG8_WAIT_V(8); PG8_WAIT_L(0); PG8_BAR; PG8_MMA(1, 0, At, B0); PG8_MMA(1, 1, At, B1); PG8_BAR; PG8_SCHED;
.LBB0_313:
	s_add_u32 s54, s4, 0x100
	s_addc_u32 vcc_lo, s5, 0
	s_mov_b32 vcc_hi, -2
	s_add_u32 s8, s18, 0x100
	s_addc_u32 s9, s19, 0
	s_add_i32 s50, 0, 0x10000
	s_cmp_eq_u32 vcc_hi, 28
	s_cselect_b32 s37, s15, s9
	s_cselect_b32 s36, s14, s8
	s_cselect_b32 s5, s17, vcc_lo
	s_cselect_b32 s4, s16, s54
	s_add_i32 s51, 0, 0x14000
	v_add_u32_e32 v156, s50, v1
	v_add_u32_e32 v172, s51, v1
	ds_read_b128 v[144:147], v156
	ds_read_b128 v[148:151], v156 offset:1024
	ds_read_b128 v[152:155], v156 offset:2048
	ds_read_b128 v[156:159], v156 offset:3072
	ds_read_b128 v[160:163], v172
	ds_read_b128 v[164:167], v172 offset:1024
	ds_read_b128 v[168:171], v172 offset:2048
	ds_read_b128 v[172:175], v172 offset:3072
	v_lshl_add_u64 v[208:209], s[18:19], 0, v[142:143]
	s_add_i32 m0, s39, 0xc000
	ds_read_b128 v[176:179], v17
	ds_read_b128 v[180:183], v17 offset:1024
	ds_read_b128 v[184:187], v17 offset:2048
	ds_read_b128 v[188:191], v17 offset:3072
	ds_read_b128 v[192:195], v17 offset:4096
	ds_read_b128 v[196:199], v17 offset:5120
	ds_read_b128 v[200:203], v17 offset:6144
	ds_read_b128 v[204:207], v17 offset:7168
	global_load_lds_dwordx4 v[208:209], off
	v_lshl_add_u64 v[208:209], s[18:19], 0, v[140:141]
	s_add_i32 m0, s39, 0xe000
	s_nop 0
	global_load_lds_dwordx4 v[208:209], off
	s_waitcnt vmcnt(8)
	s_waitcnt lgkmcnt(0)
	s_barrier
	s_setprio 1
	s_waitcnt lgkmcnt(0)
	v_mfma_f32_16x16x32_bf16 v[130:133], v[144:147], v[176:179], 0
	v_mfma_f32_16x16x32_bf16 v[102:105], v[152:155], v[176:179], 0
	v_mfma_f32_16x16x32_bf16 v[126:129], v[144:147], v[184:187], 0
	v_mfma_f32_16x16x32_bf16 v[94:97], v[152:155], v[184:187], 0
	v_mfma_f32_16x16x32_bf16 v[122:125], v[144:147], v[192:195], 0
	v_mfma_f32_16x16x32_bf16 v[90:93], v[152:155], v[192:195], 0
	v_mfma_f32_16x16x32_bf16 v[118:121], v[144:147], v[200:203], 0
	v_mfma_f32_16x16x32_bf16 v[86:89], v[152:155], v[200:203], 0
	v_mfma_f32_16x16x32_bf16 v[130:133], v[148:151], v[180:183], v[130:133]
	v_mfma_f32_16x16x32_bf16 v[102:105], v[156:159], v[180:183], v[102:105]
	v_mfma_f32_16x16x32_bf16 v[126:129], v[148:151], v[188:191], v[126:129]
	v_mfma_f32_16x16x32_bf16 v[94:97], v[156:159], v[188:191], v[94:97]
	v_mfma_f32_16x16x32_bf16 v[122:125], v[148:151], v[196:199], v[122:125]
	v_mfma_f32_16x16x32_bf16 v[90:93], v[156:159], v[196:199], v[90:93]
	v_mfma_f32_16x16x32_bf16 v[118:121], v[148:151], v[204:207], v[118:121]
	v_mfma_f32_16x16x32_bf16 v[86:89], v[156:159], v[204:207], v[86:89]
	s_setprio 0
	s_setprio 1
	v_mfma_f32_16x16x32_bf16 v[66:69], v[160:163], v[176:179], 0
	v_mfma_f32_16x16x32_bf16 v[38:41], v[168:171], v[176:179], 0
	v_mfma_f32_16x16x32_bf16 v[62:65], v[160:163], v[184:187], 0
	v_mfma_f32_16x16x32_bf16 v[30:33], v[168:171], v[184:187], 0
	v_mfma_f32_16x16x32_bf16 v[58:61], v[160:163], v[192:195], 0
	v_mfma_f32_16x16x32_bf16 v[26:29], v[168:171], v[192:195], 0
	v_mfma_f32_16x16x32_bf16 v[54:57], v[160:163], v[200:203], 0
	v_mfma_f32_16x16x32_bf16 v[22:25], v[168:171], v[200:203], 0
	v_mfma_f32_16x16x32_bf16 v[66:69], v[164:167], v[180:183], v[66:69]
	v_mfma_f32_16x16x32_bf16 v[38:41], v[172:175], v[180:183], v[38:41]
	v_mfma_f32_16x16x32_bf16 v[62:65], v[164:167], v[188:191], v[62:65]
	v_mfma_f32_16x16x32_bf16 v[30:33], v[172:175], v[188:191], v[30:33]
	v_mfma_f32_16x16x32_bf16 v[58:61], v[164:167], v[196:199], v[58:61]
	v_mfma_f32_16x16x32_bf16 v[26:29], v[172:175], v[196:199], v[26:29]
	v_mfma_f32_16x16x32_bf16 v[54:57], v[164:167], v[204:207], v[54:57]
	v_mfma_f32_16x16x32_bf16 v[22:25], v[172:175], v[204:207], v[22:25]
	s_setprio 0
	s_barrier
	s_add_i32 s18, s50, s38
	v_lshl_add_u64 v[208:209], s[4:5], 0, v[136:137]
	s_mov_b32 m0, s18
	ds_read_b128 v[176:179], v17 offset:16384
	ds_read_b128 v[180:183], v17 offset:17408
	ds_read_b128 v[184:187], v17 offset:18432
	ds_read_b128 v[188:191], v17 offset:19456
	ds_read_b128 v[192:195], v17 offset:20480
	ds_read_b128 v[196:199], v17 offset:21504
	ds_read_b128 v[200:203], v17 offset:22528
	ds_read_b128 v[204:207], v17 offset:23552
	global_load_lds_dwordx4 v[208:209], off
	s_add_i32 m0, s18, 0x2000
	s_add_u32 s18, s4, 0x84000
	v_lshl_add_u64 v[214:215], s[4:5], 0, v[14:15]
	s_addc_u32 s19, s5, 0
	s_add_i32 s50, s51, s38
	global_load_lds_dwordx4 v[214:215], off
	v_lshl_add_u64 v[216:217], s[18:19], 0, v[136:137]
	s_mov_b32 m0, s50
	v_lshl_add_u64 v[220:221], s[36:37], 0, v[134:135]
	global_load_lds_dwordx4 v[216:217], off
	v_lshl_add_u64 v[216:217], s[18:19], 0, v[14:15]
	s_add_i32 m0, s50, 0x2000
	s_nop 0
	global_load_lds_dwordx4 v[216:217], off
	v_lshl_add_u64 v[216:217], s[36:37], 0, v[138:139]
	s_mov_b32 m0, s39
	s_nop 0
	global_load_lds_dwordx4 v[216:217], off
	s_mov_b32 m0, s46
	s_nop 0
	global_load_lds_dwordx4 v[220:221], off
	s_waitcnt vmcnt(8)
	s_waitcnt lgkmcnt(0)
	s_barrier
; #define PG8_STAGE(bufoff, gbase, voff) do { _Pragma("unroll") for (int _i = 0; _i < 2; ++_i) \
;         __builtin_amdgcn_global_load_lds((const unsigned*)((const char*)(gbase) + (voff)[_i]), (PG8_LAS unsigned*)(lds + (bufoff) + ldsw + _i * 8192), 16, 0, 0); } while (0)
; #define PG8_LDA(dst, b, h) do { _Pragma("unroll") for (int m = 0; m < 4; ++m) _Pragma("unroll") for (int k = 0; k < 2; ++k) dst[m][k] = *(const PG8_LAS bf16x8*)(lds + PG8_SA(b, h) + aoff + m * 2048 + k * 1024); } while (0)
; #define PG8_LDB(dst, b, h) do { _Pragma("unroll") for (int n = 0; n < 2; ++n) _Pragma("unroll") for (int k = 0; k < 2; ++k) dst[n][k] = *(const PG8_LAS bf16x8*)(lds + PG8_SB(b, h) + boff + n * 2048 + k * 1024); } while (0)
; #define PG8_MMA(ai, bj, At, Bt) do { __builtin_amdgcn_s_setprio(1); _Pragma("unroll") for (int m = 0; m < 4; ++m) _Pragma("unroll") for (int n = 0; n < 2; ++n) _Pragma("unroll") for (int k = 0; k < 2; ++k) \
;         acc[ai][bj][m][n] = __builtin_amdgcn_mfma_f32_16x16x32_bf16(Bt[n][k], At[m][k], acc[ai][bj][m][n], 0, 0, 0); __builtin_amdgcn_s_setprio(0); } while (0)
; #define PG8_WAIT_V(n) asm volatile("s_waitcnt vmcnt(" #n ")" ::: "memory")
; #define PG8_WAIT_L(n) asm volatile("s_waitcnt lgkmcnt(" #n ")" ::: "memory")
; #define PG8_BAR __builtin_amdgcn_s_barrier()
; #define PG8_SCHED __builtin_amdgcn_sched_barrier(0)
; template <class Epi, class Sched, bool ALIGN_EPI = false, bool SP2 = false>
; __device__ __forceinline__ void gemm_phase(PG8_LAS unsigned char* lds, const Gemm g, const Sched& S, const Epi& E) {
;     ...
;             PG8_WAIT_V(8); PG8_WAIT_L(0); PG8_BAR; PG8_MMA(1, 0, At, B0); PG8_MMA(1, 1, At, B1); PG8_BAR; PG8_SCHED;
;             PG8_LDB(B0, 1, 0); PG8_LDB(B1, 1, 1); PG8_SCHED; PG8_LDA(At, 1, 0); PG8_STAGE(PG8_SA(0, 1), a2 + hstep, voffA);
;             PG8_WAIT_V(8); PG8_WAIT_L(0); PG8_BAR; PG8_MMA(0, 0, At, B0); PG8_MMA(0, 1, At, B1); PG8_BAR; PG8_SCHED;
	s_setprio 1
	s_waitcnt lgkmcnt(0)
	v_mfma_f32_16x16x32_bf16 v[114:117], v[144:147], v[176:179], 0
	v_mfma_f32_16x16x32_bf16 v[82:85], v[152:155], v[176:179], 0
	v_mfma_f32_16x16x32_bf16 v[110:113], v[144:147], v[184:187], 0
	v_mfma_f32_16x16x32_bf16 v[78:81], v[152:155], v[184:187], 0
	v_mfma_f32_16x16x32_bf16 v[106:109], v[144:147], v[192:195], 0
	v_mfma_f32_16x16x32_bf16 v[74:77], v[152:155], v[192:195], 0
	v_mfma_f32_16x16x32_bf16 v[98:101], v[144:147], v[200:203], 0
	v_mfma_f32_16x16x32_bf16 v[70:73], v[152:155], v[200:203], 0
	v_mfma_f32_16x16x32_bf16 v[114:117], v[148:151], v[180:183], v[114:117]
	v_mfma_f32_16x16x32_bf16 v[82:85], v[156:159], v[180:183], v[82:85]
	v_mfma_f32_16x16x32_bf16 v[110:113], v[148:151], v[188:191], v[110:113]
	v_mfma_f32_16x16x32_bf16 v[78:81], v[156:159], v[188:191], v[78:81]
	v_mfma_f32_16x16x32_bf16 v[106:109], v[148:151], v[196:199], v[106:109]
	v_mfma_f32_16x16x32_bf16 v[74:77], v[156:159], v[196:199], v[74:77]
	v_mfma_f32_16x16x32_bf16 v[98:101], v[148:151], v[204:207], v[98:101]
	v_mfma_f32_16x16x32_bf16 v[70:73], v[156:159], v[204:207], v[70:73]
	s_setprio 0
	s_setprio 1
	v_mfma_f32_16x16x32_bf16 v[50:53], v[160:163], v[176:179], 0
	v_mfma_f32_16x16x32_bf16 v[18:21], v[168:171], v[176:179], 0
	v_mfma_f32_16x16x32_bf16 v[46:49], v[160:163], v[184:187], 0
	v_mfma_f32_16x16x32_bf16 v[10:13], v[168:171], v[184:187], 0
	v_mfma_f32_16x16x32_bf16 v[42:45], v[160:163], v[192:195], 0
	v_mfma_f32_16x16x32_bf16 v[6:9], v[168:171], v[192:195], 0
	v_mfma_f32_16x16x32_bf16 v[34:37], v[160:163], v[200:203], 0
	v_mfma_f32_16x16x32_bf16 v[2:5], v[168:171], v[200:203], 0
	v_mfma_f32_16x16x32_bf16 v[50:53], v[164:167], v[180:183], v[50:53]
	v_mfma_f32_16x16x32_bf16 v[18:21], v[172:175], v[180:183], v[18:21]
	v_mfma_f32_16x16x32_bf16 v[46:49], v[164:167], v[188:191], v[46:49]
	v_mfma_f32_16x16x32_bf16 v[10:13], v[172:175], v[188:191], v[10:13]
	v_mfma_f32_16x16x32_bf16 v[42:45], v[164:167], v[196:199], v[42:45]
	v_mfma_f32_16x16x32_bf16 v[6:9], v[172:175], v[196:199], v[6:9]
	v_mfma_f32_16x16x32_bf16 v[34:37], v[164:167], v[204:207], v[34:37]
	v_mfma_f32_16x16x32_bf16 v[2:5], v[172:175], v[204:207], v[2:5]
	s_setprio 0
	s_barrier
	s_add_i32 s50, 0, 0x18000
	s_add_i32 s51, 0, 0x1c000
	v_add_u32_e32 v156, s50, v1
	v_add_u32_e32 v172, s51, v1
	ds_read_b128 v[144:147], v156
	ds_read_b128 v[148:151], v156 offset:1024
	ds_read_b128 v[152:155], v156 offset:2048
	ds_read_b128 v[156:159], v156 offset:3072
	ds_read_b128 v[160:163], v172
	ds_read_b128 v[164:167], v172 offset:1024
	ds_read_b128 v[168:171], v172 offset:2048
	ds_read_b128 v[172:175], v172 offset:3072
	s_add_u32 s18, s36, 0x84000
	s_addc_u32 s19, s37, 0
	s_mov_b32 m0, s64
	v_lshl_add_u64 v[222:223], s[18:19], 0, v[138:139]
	ds_read_b128 v[176:179], v17 offset:32768
	ds_read_b128 v[180:183], v17 offset:33792
	ds_read_b128 v[184:187], v17 offset:34816
	ds_read_b128 v[188:191], v17 offset:35840
	ds_read_b128 v[192:195], v17 offset:36864
	ds_read_b128 v[196:199], v17 offset:37888
	ds_read_b128 v[200:203], v17 offset:38912
	ds_read_b128 v[204:207], v17 offset:39936
	global_load_lds_dwordx4 v[222:223], off
	v_lshl_add_u64 v[222:223], s[18:19], 0, v[134:135]
	s_mov_b32 m0, s65
	s_nop 0
	global_load_lds_dwordx4 v[222:223], off
	s_waitcnt vmcnt(8)
	s_waitcnt lgkmcnt(0)
	s_barrier
	s_setprio 1
	s_waitcnt lgkmcnt(0)
	v_mfma_f32_16x16x32_bf16 v[130:133], v[144:147], v[176:179], v[130:133]
	v_mfma_f32_16x16x32_bf16 v[102:105], v[152:155], v[176:179], v[102:105]
	v_mfma_f32_16x16x32_bf16 v[126:129], v[144:147], v[184:187], v[126:129]
	v_mfma_f32_16x16x32_bf16 v[94:97], v[152:155], v[184:187], v[94:97]
	v_mfma_f32_16x16x32_bf16 v[122:125], v[144:147], v[192:195], v[122:125]
	v_mfma_f32_16x16x32_bf16 v[90:93], v[152:155], v[192:195], v[90:93]
	v_mfma_f32_16x16x32_bf16 v[118:121], v[144:147], v[200:203], v[118:121]
	v_mfma_f32_16x16x32_bf16 v[86:89], v[152:155], v[200:203], v[86:89]
	v_mfma_f32_16x16x32_bf16 v[130:133], v[148:151], v[180:183], v[130:133]
	v_mfma_f32_16x16x32_bf16 v[102:105], v[156:159], v[180:183], v[102:105]
	v_mfma_f32_16x16x32_bf16 v[126:129], v[148:151], v[188:191], v[126:129]
	v_mfma_f32_16x16x32_bf16 v[94:97], v[156:159], v[188:191], v[94:97]
	v_mfma_f32_16x16x32_bf16 v[122:125], v[148:151], v[196:199], v[122:125]
	v_mfma_f32_16x16x32_bf16 v[90:93], v[156:159], v[196:199], v[90:93]
	v_mfma_f32_16x16x32_bf16 v[118:121], v[148:151], v[204:207], v[118:121]
	v_mfma_f32_16x16x32_bf16 v[86:89], v[156:159], v[204:207], v[86:89]
	s_setprio 0
	s_setprio 1
	v_mfma_f32_16x16x32_bf16 v[66:69], v[160:163], v[176:179], v[66:69]
	v_mfma_f32_16x16x32_bf16 v[38:41], v[168:171], v[176:179], v[38:41]
	v_mfma_f32_16x16x32_bf16 v[62:65], v[160:163], v[184:187], v[62:65]
	v_mfma_f32_16x16x32_bf16 v[30:33], v[168:171], v[184:187], v[30:33]
	v_mfma_f32_16x16x32_bf16 v[58:61], v[160:163], v[192:195], v[58:61]
	v_mfma_f32_16x16x32_bf16 v[26:29], v[168:171], v[192:195], v[26:29]
	v_mfma_f32_16x16x32_bf16 v[54:57], v[160:163], v[200:203], v[54:57]
	v_mfma_f32_16x16x32_bf16 v[22:25], v[168:171], v[200:203], v[22:25]
	v_mfma_f32_16x16x32_bf16 v[66:69], v[164:167], v[180:183], v[66:69]
	v_mfma_f32_16x16x32_bf16 v[38:41], v[172:175], v[180:183], v[38:41]
	v_mfma_f32_16x16x32_bf16 v[62:65], v[164:167], v[188:191], v[62:65]
	v_mfma_f32_16x16x32_bf16 v[30:33], v[172:175], v[188:191], v[30:33]
	v_mfma_f32_16x16x32_bf16 v[58:61], v[164:167], v[196:199], v[58:61]
	v_mfma_f32_16x16x32_bf16 v[26:29], v[172:175], v[196:199], v[26:29]
	v_mfma_f32_16x16x32_bf16 v[54:57], v[164:167], v[204:207], v[54:57]
	v_mfma_f32_16x16x32_bf16 v[22:25], v[172:175], v[204:207], v[22:25]
	s_setprio 0
	s_barrier
; #define PG8_STAGE(bufoff, gbase, voff) do { _Pragma("unroll") for (int _i = 0; _i < 2; ++_i) \
;         __builtin_amdgcn_global_load_lds((const unsigned*)((const char*)(gbase) + (voff)[_i]), (PG8_LAS unsigned*)(lds + (bufoff) + ldsw + _i * 8192), 16, 0, 0); } while (0)
; #define PG8_LDA(dst, b, h) do { _Pragma("unroll") for (int m = 0; m < 4; ++m) _Pragma("unroll") for (int k = 0; k < 2; ++k) dst[m][k] = *(const PG8_LAS bf16x8*)(lds + PG8_SA(b, h) + aoff + m * 2048 + k * 1024); } while (0)
; #define PG8_MMA(ai, bj, At, Bt) do { __builtin_amdgcn_s_setprio(1); _Pragma("unroll") for (int m = 0; m < 4; ++m) _Pragma("unroll") for (int n = 0; n < 2; ++n) _Pragma("unroll") for (int k = 0; k < 2; ++k) \
;         acc[ai][bj][m][n] = __builtin_amdgcn_mfma_f32_16x16x32_bf16(Bt[n][k], At[m][k], acc[ai][bj][m][n], 0, 0, 0); __builtin_amdgcn_s_setprio(0); } while (0)
; #define PG8_WAIT_V(n) asm volatile("s_waitcnt vmcnt(" #n ")" ::: "memory")
; #define PG8_WAIT_L(n) asm volatile("s_waitcnt lgkmcnt(" #n ")" ::: "memory")
; #define PG8_BAR __builtin_amdgcn_s_barrier()
; #define PG8_SCHED __builtin_amdgcn_sched_barrier(0)
; template <class Epi, class Sched, bool ALIGN_EPI = false, bool SP2 = false>
; __device__ __forceinline__ void gemm_phase(PG8_LAS unsigned char* lds, const Gemm g, const Sched& S, const Epi& E) {
;     ...
;             PG8_LDA(At, 1, 1); PG8_STAGE(PG8_SB(1, 0), b3, voffB); PG8_STAGE(PG8_SB(1, 1), b3 + hstep, voffB); PG8_STAGE(PG8_SA(1, 0), a3, voffA);
;             PG8_WAIT_V(8); PG8_WAIT_L(0); PG8_BAR; PG8_MMA(1, 0, At, B0); PG8_MMA(1, 1, At, B1); PG8_BAR; PG8_SCHED;
	s_add_i32 s18, s50, s38
	v_lshl_add_u64 v[208:209], v[208:209], 0, s[48:49]
	s_mov_b32 m0, s18
	ds_read_b128 v[176:179], v17 offset:49152
	ds_read_b128 v[180:183], v17 offset:50176
	ds_read_b128 v[184:187], v17 offset:51200
	ds_read_b128 v[188:191], v17 offset:52224
	ds_read_b128 v[192:195], v17 offset:53248
	ds_read_b128 v[196:199], v17 offset:54272
	ds_read_b128 v[200:203], v17 offset:55296
	ds_read_b128 v[204:207], v17 offset:56320
	global_load_lds_dwordx4 v[208:209], off
	s_add_i32 m0, s18, 0x2000
	s_add_u32 s4, s4, 0x84080
	v_lshl_add_u64 v[208:209], v[214:215], 0, s[48:49]
	s_addc_u32 s5, s5, 0
	s_add_i32 s18, s51, s38
	global_load_lds_dwordx4 v[208:209], off
	v_lshl_add_u64 v[208:209], s[4:5], 0, v[136:137]
	s_mov_b32 m0, s18
	s_nop 0
	global_load_lds_dwordx4 v[208:209], off
	v_lshl_add_u64 v[208:209], s[4:5], 0, v[14:15]
	s_add_i32 m0, s18, 0x2000
	s_nop 0
	global_load_lds_dwordx4 v[208:209], off
	v_lshl_add_u64 v[208:209], v[216:217], 0, s[48:49]
	s_mov_b32 m0, s96
	s_nop 0
	global_load_lds_dwordx4 v[208:209], off
	v_lshl_add_u64 v[208:209], v[220:221], 0, s[48:49]
	s_mov_b32 m0, s97
	s_nop 0
	global_load_lds_dwordx4 v[208:209], off
	s_waitcnt vmcnt(8)
	s_waitcnt lgkmcnt(0)
	s_barrier
	s_setprio 1
	s_waitcnt lgkmcnt(0)
	v_mfma_f32_16x16x32_bf16 v[114:117], v[144:147], v[176:179], v[114:117]
	v_mfma_f32_16x16x32_bf16 v[82:85], v[152:155], v[176:179], v[82:85]
	v_mfma_f32_16x16x32_bf16 v[110:113], v[144:147], v[184:187], v[110:113]
	v_mfma_f32_16x16x32_bf16 v[78:81], v[152:155], v[184:187], v[78:81]
	v_mfma_f32_16x16x32_bf16 v[106:109], v[144:147], v[192:195], v[106:109]
	v_mfma_f32_16x16x32_bf16 v[74:77], v[152:155], v[192:195], v[74:77]
	v_mfma_f32_16x16x32_bf16 v[98:101], v[144:147], v[200:203], v[98:101]
	v_mfma_f32_16x16x32_bf16 v[70:73], v[152:155], v[200:203], v[70:73]
	v_mfma_f32_16x16x32_bf16 v[114:117], v[148:151], v[180:183], v[114:117]
	v_mfma_f32_16x16x32_bf16 v[82:85], v[156:159], v[180:183], v[82:85]
	v_mfma_f32_16x16x32_bf16 v[110:113], v[148:151], v[188:191], v[110:113]
	v_mfma_f32_16x16x32_bf16 v[78:81], v[156:159], v[188:191], v[78:81]
	v_mfma_f32_16x16x32_bf16 v[106:109], v[148:151], v[196:199], v[106:109]
	v_mfma_f32_16x16x32_bf16 v[74:77], v[156:159], v[196:199], v[74:77]
	v_mfma_f32_16x16x32_bf16 v[98:101], v[148:151], v[204:207], v[98:101]
	v_mfma_f32_16x16x32_bf16 v[70:73], v[156:159], v[204:207], v[70:73]
	s_setprio 0
	s_setprio 1
	v_mfma_f32_16x16x32_bf16 v[50:53], v[160:163], v[176:179], v[50:53]
	v_mfma_f32_16x16x32_bf16 v[18:21], v[168:171], v[176:179], v[18:21]
	v_mfma_f32_16x16x32_bf16 v[46:49], v[160:163], v[184:187], v[46:49]
	v_mfma_f32_16x16x32_bf16 v[10:13], v[168:171], v[184:187], v[10:13]
	v_mfma_f32_16x16x32_bf16 v[42:45], v[160:163], v[192:195], v[42:45]
	v_mfma_f32_16x16x32_bf16 v[6:9], v[168:171], v[192:195], v[6:9]
	v_mfma_f32_16x16x32_bf16 v[34:37], v[160:163], v[200:203], v[34:37]
	v_mfma_f32_16x16x32_bf16 v[2:5], v[168:171], v[200:203], v[2:5]
	v_mfma_f32_16x16x32_bf16 v[50:53], v[164:167], v[180:183], v[50:53]
	v_mfma_f32_16x16x32_bf16 v[18:21], v[172:175], v[180:183], v[18:21]
	v_mfma_f32_16x16x32_bf16 v[46:49], v[164:167], v[188:191], v[46:49]
	v_mfma_f32_16x16x32_bf16 v[10:13], v[172:175], v[188:191], v[10:13]
	v_mfma_f32_16x16x32_bf16 v[42:45], v[164:167], v[196:199], v[42:45]
	v_mfma_f32_16x16x32_bf16 v[6:9], v[172:175], v[196:199], v[6:9]
	v_mfma_f32_16x16x32_bf16 v[34:37], v[164:167], v[204:207], v[34:37]
	v_mfma_f32_16x16x32_bf16 v[2:5], v[172:175], v[204:207], v[2:5]
	s_setprio 0
	s_barrier
	s_add_i32 vcc_hi, vcc_hi, 2
	s_add_u32 s54, s54, 0x100
	s_addc_u32 vcc_lo, vcc_lo, 0
	s_cmp_gt_u32 vcc_hi, 29
	s_mov_b64 s[18:19], s[8:9]
	s_cbranch_scc0 .LBB0_314
	s_branch .Lgemm_exit_b

; #define PG8_BAR __builtin_amdgcn_s_barrier()
; template <class Epi, class Sched, bool ALIGN_EPI = false, bool SP2 = false>
; __device__ __forceinline__ void gemm_phase(PG8_LAS unsigned char* lds, const Gemm g, const Sched& S, const Epi& E) {
;     ...
;         if constexpr (ALIGN_EPI) { if (wr == 0) PG8_BAR; }
.Lgemm_exit_b:
	s_and_b64 vcc, exec, s[12:13]
	s_cbranch_vccz .LBB0_317
	s_barrier

; #define PG8_STAGE(bufoff, gbase, voff) do { _Pragma("unroll") for (int _i = 0; _i < 2; ++_i) \
;         __builtin_amdgcn_global_load_lds((const unsigned*)((const char*)(gbase) + (voff)[_i]), (PG8_LAS unsigned*)(lds + (bufoff) + ldsw + _i * 8192), 16, 0, 0); } while (0)
; #define PG8_LDA(dst, b, h) do { _Pragma("unroll") for (int m = 0; m < 4; ++m) _Pragma("unroll") for (int k = 0; k < 2; ++k) dst[m][k] = *(const PG8_LAS bf16x8*)(lds + PG8_SA(b, h) + aoff + m * 2048 + k * 1024); } while (0)
; #define PG8_LDB(dst, b, h) do { _Pragma("unroll") for (int n = 0; n < 2; ++n) _Pragma("unroll") for (int k = 0; k < 2; ++k) dst[n][k] = *(const PG8_LAS bf16x8*)(lds + PG8_SB(b, h) + boff + n * 2048 + k * 1024); } while (0)
; #define PG8_WAIT_V(n) asm volatile("s_waitcnt vmcnt(" #n ")" ::: "memory")
; #define PG8_WAIT_L(n) asm volatile("s_waitcnt lgkmcnt(" #n ")" ::: "memory")
; #define PG8_BAR __builtin_amdgcn_s_barrier()
; template <class Epi, class Sched, bool ALIGN_EPI = false, bool SP2 = false>
; __device__ __forceinline__ void gemm_phase(PG8_LAS unsigned char* lds, const Gemm g, const Sched& S, const Epi& E) {
;     ...
;     f32x4 acc[2][2][4][2];
; #pragma unroll
;     for (int a = 0; a < 2; ++a)
; #pragma unroll
;         for (int b = 0; b < 2; ++b)
; #pragma unroll
;             for (int m = 0; m < 4; ++m)
; #pragma unroll
;                 for (int n = 0; n < 2; ++n) acc[a][b][m][n] = (f32x4){0.f, 0.f, 0.f, 0.f};
;     ...
;         for (int t = 0; t < nt; t += 2) {
;             const bool last = (t == nt - 2);
;             const char* a1 = cA + (size_t)(t + 1) * kstep;
;             const char* a2 = last ? nA : cA + (size_t)(t + 2) * kstep; const char* b2 = last ? nB : cB + (size_t)(t + 2) * kstep;
;             const char* a3 = a2 + kstep; const char* b3 = b2 + kstep;
;             if (last && has_next) S.a_ready(nxt);
;             if constexpr (SP2) {
;             PG8_LDB(B0, 0, 0); PG8_LDB(B1, 0, 1); PG8_SCHED; PG8_LDA(At, 0, 0); PG8_STAGE(PG8_SA(1, 1), a1 + hstep, voffA);
;             PG8_WAIT_V(8); PG8_WAIT_L(0); PG8_BAR; PG8_MMA(0, 0, At, B0); PG8_MMA(0, 1, At, B1); PG8_BAR; PG8_SCHED;
;             PG8_LDA(At, 0, 1); PG8_STAGE(PG8_SB(0, 0), b2, voffB); PG8_STAGE(PG8_SB(0, 1), b2 + hstep, voffB); PG8_STAGE(PG8_SA(0, 0), a2, voffA);
;             PG8_WAIT_V(8); PG8_WAIT_L(0); PG8_BAR; PG8_MMA(1, 0, At, B0); PG8_MMA(1, 1, At, B1); PG8_BAR; PG8_SCHED;
.LBB0_379:
	s_add_u32 s94, s36, 0x100
	s_addc_u32 s95, s37, 0
	s_add_u32 s36, s38, 0x80
	s_addc_u32 s37, s39, 0
	s_mov_b32 s4, 0
	s_add_i32 s38, s4, 2
	s_add_u32 s39, s36, 0x80
	s_addc_u32 s5, s37, 0
	s_add_i32 vcc_lo, 0, 0x10000
	s_cmp_eq_u32 s90, s4
	s_cselect_b32 s5, s9, s5
	s_cselect_b32 s4, s8, s39
	s_cselect_b32 s97, s19, s95
	s_cselect_b32 s96, s18, s94
	s_add_i32 s39, 0, 0x14000
	v_add_u32_e32 v156, vcc_lo, v1
	v_add_u32_e32 v172, s39, v1
	ds_read_b128 v[144:147], v156
	ds_read_b128 v[148:151], v156 offset:1024
	ds_read_b128 v[152:155], v156 offset:2048
	ds_read_b128 v[156:159], v156 offset:3072
	ds_read_b128 v[160:163], v172
	ds_read_b128 v[164:167], v172 offset:1024
	ds_read_b128 v[168:171], v172 offset:2048
	ds_read_b128 v[172:175], v172 offset:3072
	v_lshl_add_u64 v[208:209], s[36:37], 0, v[142:143]
	s_add_i32 m0, s41, 0xc000
	ds_read_b128 v[176:179], v17
	ds_read_b128 v[180:183], v17 offset:1024
	ds_read_b128 v[184:187], v17 offset:2048
	ds_read_b128 v[188:191], v17 offset:3072
	ds_read_b128 v[192:195], v17 offset:4096
	ds_read_b128 v[196:199], v17 offset:5120
	ds_read_b128 v[200:203], v17 offset:6144
	ds_read_b128 v[204:207], v17 offset:7168
	global_load_lds_dwordx4 v[208:209], off
	v_lshl_add_u64 v[208:209], s[36:37], 0, v[140:141]
	s_add_i32 m0, s41, 0xe000
	s_nop 0
	global_load_lds_dwordx4 v[208:209], off
	s_waitcnt vmcnt(8)
	s_waitcnt lgkmcnt(0)
	s_barrier
	s_setprio 1
	s_waitcnt lgkmcnt(0)
	v_mfma_f32_16x16x32_bf16 v[130:133], v[144:147], v[176:179], 0
	v_mfma_f32_16x16x32_bf16 v[126:129], v[152:155], v[176:179], 0
	v_mfma_f32_16x16x32_bf16 v[122:125], v[144:147], v[184:187], 0
	v_mfma_f32_16x16x32_bf16 v[114:117], v[152:155], v[184:187], 0
	v_mfma_f32_16x16x32_bf16 v[106:109], v[144:147], v[192:195], 0
	v_mfma_f32_16x16x32_bf16 v[98:101], v[152:155], v[192:195], 0
	v_mfma_f32_16x16x32_bf16 v[90:93], v[144:147], v[200:203], 0
	v_mfma_f32_16x16x32_bf16 v[82:85], v[152:155], v[200:203], 0
	v_mfma_f32_16x16x32_bf16 v[130:133], v[148:151], v[180:183], v[130:133]
	v_mfma_f32_16x16x32_bf16 v[126:129], v[156:159], v[180:183], v[126:129]
	v_mfma_f32_16x16x32_bf16 v[122:125], v[148:151], v[188:191], v[122:125]
	v_mfma_f32_16x16x32_bf16 v[114:117], v[156:159], v[188:191], v[114:117]
	v_mfma_f32_16x16x32_bf16 v[106:109], v[148:151], v[196:199], v[106:109]
	v_mfma_f32_16x16x32_bf16 v[98:101], v[156:159], v[196:199], v[98:101]
	v_mfma_f32_16x16x32_bf16 v[90:93], v[148:151], v[204:207], v[90:93]
	v_mfma_f32_16x16x32_bf16 v[82:85], v[156:159], v[204:207], v[82:85]
	s_setprio 0
	s_setprio 1
	v_mfma_f32_16x16x32_bf16 v[118:121], v[160:163], v[176:179], 0
	v_mfma_f32_16x16x32_bf16 v[110:113], v[168:171], v[176:179], 0
	v_mfma_f32_16x16x32_bf16 v[102:105], v[160:163], v[184:187], 0
	v_mfma_f32_16x16x32_bf16 v[94:97], v[168:171], v[184:187], 0
	v_mfma_f32_16x16x32_bf16 v[86:89], v[160:163], v[192:195], 0
	v_mfma_f32_16x16x32_bf16 v[78:81], v[168:171], v[192:195], 0
	v_mfma_f32_16x16x32_bf16 v[74:77], v[160:163], v[200:203], 0
	v_mfma_f32_16x16x32_bf16 v[70:73], v[168:171], v[200:203], 0
	v_mfma_f32_16x16x32_bf16 v[118:121], v[164:167], v[180:183], v[118:121]
	v_mfma_f32_16x16x32_bf16 v[110:113], v[172:175], v[180:183], v[110:113]
	v_mfma_f32_16x16x32_bf16 v[102:105], v[164:167], v[188:191], v[102:105]
	v_mfma_f32_16x16x32_bf16 v[94:97], v[172:175], v[188:191], v[94:97]
	v_mfma_f32_16x16x32_bf16 v[86:89], v[164:167], v[196:199], v[86:89]
	v_mfma_f32_16x16x32_bf16 v[78:81], v[172:175], v[196:199], v[78:81]
	v_mfma_f32_16x16x32_bf16 v[74:77], v[164:167], v[204:207], v[74:77]
	v_mfma_f32_16x16x32_bf16 v[70:73], v[172:175], v[204:207], v[70:73]
	s_setprio 0
	s_barrier
	s_add_i32 vcc_lo, vcc_lo, s64
	v_lshl_add_u64 v[208:209], s[96:97], 0, v[136:137]
	s_mov_b32 m0, vcc_lo
	ds_read_b128 v[176:179], v17 offset:16384
	ds_read_b128 v[180:183], v17 offset:17408
	ds_read_b128 v[184:187], v17 offset:18432
	ds_read_b128 v[188:191], v17 offset:19456
	ds_read_b128 v[192:195], v17 offset:20480
	ds_read_b128 v[196:199], v17 offset:21504
	ds_read_b128 v[200:203], v17 offset:22528
	ds_read_b128 v[204:207], v17 offset:23552
	global_load_lds_dwordx4 v[208:209], off
	s_add_i32 m0, vcc_lo, 0x2000
	v_lshl_add_u64 v[214:215], s[96:97], 0, v[14:15]
	s_add_u32 s96, s96, s54
	s_addc_u32 s97, s97, 0
	s_add_i32 s39, s39, s64
	global_load_lds_dwordx4 v[214:215], off
	v_lshl_add_u64 v[216:217], s[96:97], 0, v[136:137]
	s_mov_b32 m0, s39
	v_lshl_add_u64 v[220:221], s[96:97], 0, v[14:15]
	global_load_lds_dwordx4 v[216:217], off
	s_add_i32 m0, s39, 0x2000
	v_lshl_add_u64 v[222:223], s[4:5], 0, v[138:139]
	global_load_lds_dwordx4 v[220:221], off
	s_mov_b32 m0, s41
	v_lshl_add_u64 v[232:233], s[4:5], 0, v[134:135]
	global_load_lds_dwordx4 v[222:223], off
	s_mov_b32 m0, s43
	s_nop 0
	global_load_lds_dwordx4 v[232:233], off
	s_waitcnt vmcnt(8)
	s_waitcnt lgkmcnt(0)
	s_barrier
; #define PG8_STAGE(bufoff, gbase, voff) do { _Pragma("unroll") for (int _i = 0; _i < 2; ++_i) \
;         __builtin_amdgcn_global_load_lds((const unsigned*)((const char*)(gbase) + (voff)[_i]), (PG8_LAS unsigned*)(lds + (bufoff) + ldsw + _i * 8192), 16, 0, 0); } while (0)
; #define PG8_LDA(dst, b, h) do { _Pragma("unroll") for (int m = 0; m < 4; ++m) _Pragma("unroll") for (int k = 0; k < 2; ++k) dst[m][k] = *(const PG8_LAS bf16x8*)(lds + PG8_SA(b, h) + aoff + m * 2048 + k * 1024); } while (0)
; #define PG8_LDB(dst, b, h) do { _Pragma("unroll") for (int n = 0; n < 2; ++n) _Pragma("unroll") for (int k = 0; k < 2; ++k) dst[n][k] = *(const PG8_LAS bf16x8*)(lds + PG8_SB(b, h) + boff + n * 2048 + k * 1024); } while (0)
; #define PG8_MMA(ai, bj, At, Bt) do { __builtin_amdgcn_s_setprio(1); _Pragma("unroll") for (int m = 0; m < 4; ++m) _Pragma("unroll") for (int n = 0; n < 2; ++n) _Pragma("unroll") for (int k = 0; k < 2; ++k) \
;         acc[ai][bj][m][n] = __builtin_amdgcn_mfma_f32_16x16x32_bf16(Bt[n][k], At[m][k], acc[ai][bj][m][n], 0, 0, 0); __builtin_amdgcn_s_setprio(0); } while (0)
; #define PG8_WAIT_V(n) asm volatile("s_waitcnt vmcnt(" #n ")" ::: "memory")
; #define PG8_WAIT_L(n) asm volatile("s_waitcnt lgkmcnt(" #n ")" ::: "memory")
; #define PG8_BAR __builtin_amdgcn_s_barrier()
; #define PG8_SCHED __builtin_amdgcn_sched_barrier(0)
; template <class Epi, class Sched, bool ALIGN_EPI = false, bool SP2 = false>
; __device__ __forceinline__ void gemm_phase(PG8_LAS unsigned char* lds, const Gemm g, const Sched& S, const Epi& E) {
;     ...
;             PG8_WAIT_V(8); PG8_WAIT_L(0); PG8_BAR; PG8_MMA(1, 0, At, B0); PG8_MMA(1, 1, At, B1); PG8_BAR; PG8_SCHED;
;             PG8_LDB(B0, 1, 0); PG8_LDB(B1, 1, 1); PG8_SCHED; PG8_LDA(At, 1, 0); PG8_STAGE(PG8_SA(0, 1), a2 + hstep, voffA);
;             PG8_WAIT_V(8); PG8_WAIT_L(0); PG8_BAR; PG8_MMA(0, 0, At, B0); PG8_MMA(0, 1, At, B1); PG8_BAR; PG8_SCHED;
	s_setprio 1
	s_waitcnt lgkmcnt(0)
	v_mfma_f32_16x16x32_bf16 v[66:69], v[144:147], v[176:179], 0
	v_mfma_f32_16x16x32_bf16 v[62:65], v[152:155], v[176:179], 0
	v_mfma_f32_16x16x32_bf16 v[58:61], v[144:147], v[184:187], 0
	v_mfma_f32_16x16x32_bf16 v[50:53], v[152:155], v[184:187], 0
	v_mfma_f32_16x16x32_bf16 v[42:45], v[144:147], v[192:195], 0
	v_mfma_f32_16x16x32_bf16 v[34:37], v[152:155], v[192:195], 0
	v_mfma_f32_16x16x32_bf16 v[26:29], v[144:147], v[200:203], 0
	v_mfma_f32_16x16x32_bf16 v[18:21], v[152:155], v[200:203], 0
	v_mfma_f32_16x16x32_bf16 v[66:69], v[148:151], v[180:183], v[66:69]
	v_mfma_f32_16x16x32_bf16 v[62:65], v[156:159], v[180:183], v[62:65]
	v_mfma_f32_16x16x32_bf16 v[58:61], v[148:151], v[188:191], v[58:61]
	v_mfma_f32_16x16x32_bf16 v[50:53], v[156:159], v[188:191], v[50:53]
	v_mfma_f32_16x16x32_bf16 v[42:45], v[148:151], v[196:199], v[42:45]
	v_mfma_f32_16x16x32_bf16 v[34:37], v[156:159], v[196:199], v[34:37]
	v_mfma_f32_16x16x32_bf16 v[26:29], v[148:151], v[204:207], v[26:29]
	v_mfma_f32_16x16x32_bf16 v[18:21], v[156:159], v[204:207], v[18:21]
	s_setprio 0
	s_setprio 1
	v_mfma_f32_16x16x32_bf16 v[54:57], v[160:163], v[176:179], 0
	v_mfma_f32_16x16x32_bf16 v[46:49], v[168:171], v[176:179], 0
	v_mfma_f32_16x16x32_bf16 v[38:41], v[160:163], v[184:187], 0
	v_mfma_f32_16x16x32_bf16 v[30:33], v[168:171], v[184:187], 0
	v_mfma_f32_16x16x32_bf16 v[22:25], v[160:163], v[192:195], 0
	v_mfma_f32_16x16x32_bf16 v[10:13], v[168:171], v[192:195], 0
	v_mfma_f32_16x16x32_bf16 v[6:9], v[160:163], v[200:203], 0
	v_mfma_f32_16x16x32_bf16 v[2:5], v[168:171], v[200:203], 0
	v_mfma_f32_16x16x32_bf16 v[54:57], v[164:167], v[180:183], v[54:57]
	v_mfma_f32_16x16x32_bf16 v[46:49], v[172:175], v[180:183], v[46:49]
	v_mfma_f32_16x16x32_bf16 v[38:41], v[164:167], v[188:191], v[38:41]
	v_mfma_f32_16x16x32_bf16 v[30:33], v[172:175], v[188:191], v[30:33]
	v_mfma_f32_16x16x32_bf16 v[22:25], v[164:167], v[196:199], v[22:25]
	v_mfma_f32_16x16x32_bf16 v[10:13], v[172:175], v[196:199], v[10:13]
	v_mfma_f32_16x16x32_bf16 v[6:9], v[164:167], v[204:207], v[6:9]
	v_mfma_f32_16x16x32_bf16 v[2:5], v[172:175], v[204:207], v[2:5]
	s_setprio 0
	s_barrier
	s_add_i32 s39, 0, 0x18000
	s_add_i32 s96, 0, 0x1c000
	v_add_u32_e32 v156, s39, v1
	v_add_u32_e32 v172, s96, v1
	ds_read_b128 v[144:147], v156
	ds_read_b128 v[148:151], v156 offset:1024
	ds_read_b128 v[152:155], v156 offset:2048
	ds_read_b128 v[156:159], v156 offset:3072
	ds_read_b128 v[160:163], v172
	ds_read_b128 v[164:167], v172 offset:1024
	ds_read_b128 v[168:171], v172 offset:2048
	ds_read_b128 v[172:175], v172 offset:3072
	s_add_u32 s4, s4, s54
	s_addc_u32 s5, s5, 0
	s_mov_b32 m0, s65
	v_lshl_add_u64 v[234:235], s[4:5], 0, v[138:139]
	ds_read_b128 v[176:179], v17 offset:32768
	ds_read_b128 v[180:183], v17 offset:33792
	ds_read_b128 v[184:187], v17 offset:34816
	ds_read_b128 v[188:191], v17 offset:35840
	ds_read_b128 v[192:195], v17 offset:36864
	ds_read_b128 v[196:199], v17 offset:37888
	ds_read_b128 v[200:203], v17 offset:38912
	ds_read_b128 v[204:207], v17 offset:39936
	global_load_lds_dwordx4 v[234:235], off
	v_lshl_add_u64 v[234:235], s[4:5], 0, v[134:135]
	s_mov_b32 m0, s68
	s_nop 0
	global_load_lds_dwordx4 v[234:235], off
	s_waitcnt vmcnt(8)
	s_waitcnt lgkmcnt(0)
	s_barrier
	s_setprio 1
	s_waitcnt lgkmcnt(0)
	v_mfma_f32_16x16x32_bf16 v[130:133], v[144:147], v[176:179], v[130:133]
	v_mfma_f32_16x16x32_bf16 v[126:129], v[152:155], v[176:179], v[126:129]
	v_mfma_f32_16x16x32_bf16 v[122:125], v[144:147], v[184:187], v[122:125]
	v_mfma_f32_16x16x32_bf16 v[114:117], v[152:155], v[184:187], v[114:117]
	v_mfma_f32_16x16x32_bf16 v[106:109], v[144:147], v[192:195], v[106:109]
	v_mfma_f32_16x16x32_bf16 v[98:101], v[152:155], v[192:195], v[98:101]
	v_mfma_f32_16x16x32_bf16 v[90:93], v[144:147], v[200:203], v[90:93]
	v_mfma_f32_16x16x32_bf16 v[82:85], v[152:155], v[200:203], v[82:85]
	v_mfma_f32_16x16x32_bf16 v[130:133], v[148:151], v[180:183], v[130:133]
	v_mfma_f32_16x16x32_bf16 v[126:129], v[156:159], v[180:183], v[126:129]
	v_mfma_f32_16x16x32_bf16 v[122:125], v[148:151], v[188:191], v[122:125]
	v_mfma_f32_16x16x32_bf16 v[114:117], v[156:159], v[188:191], v[114:117]
	v_mfma_f32_16x16x32_bf16 v[106:109], v[148:151], v[196:199], v[106:109]
	v_mfma_f32_16x16x32_bf16 v[98:101], v[156:159], v[196:199], v[98:101]
	v_mfma_f32_16x16x32_bf16 v[90:93], v[148:151], v[204:207], v[90:93]
	v_mfma_f32_16x16x32_bf16 v[82:85], v[156:159], v[204:207], v[82:85]
	s_setprio 0
	s_setprio 1
	v_mfma_f32_16x16x32_bf16 v[118:121], v[160:163], v[176:179], v[118:121]
	v_mfma_f32_16x16x32_bf16 v[110:113], v[168:171], v[176:179], v[110:113]
	v_mfma_f32_16x16x32_bf16 v[102:105], v[160:163], v[184:187], v[102:105]
	v_mfma_f32_16x16x32_bf16 v[94:97], v[168:171], v[184:187], v[94:97]
	v_mfma_f32_16x16x32_bf16 v[86:89], v[160:163], v[192:195], v[86:89]
	v_mfma_f32_16x16x32_bf16 v[78:81], v[168:171], v[192:195], v[78:81]
	v_mfma_f32_16x16x32_bf16 v[74:77], v[160:163], v[200:203], v[74:77]
	v_mfma_f32_16x16x32_bf16 v[70:73], v[168:171], v[200:203], v[70:73]
	v_mfma_f32_16x16x32_bf16 v[118:121], v[164:167], v[180:183], v[118:121]
	v_mfma_f32_16x16x32_bf16 v[110:113], v[172:175], v[180:183], v[110:113]
	v_mfma_f32_16x16x32_bf16 v[102:105], v[164:167], v[188:191], v[102:105]
	v_mfma_f32_16x16x32_bf16 v[94:97], v[172:175], v[188:191], v[94:97]
	v_mfma_f32_16x16x32_bf16 v[86:89], v[164:167], v[196:199], v[86:89]
	v_mfma_f32_16x16x32_bf16 v[78:81], v[172:175], v[196:199], v[78:81]
	v_mfma_f32_16x16x32_bf16 v[74:77], v[164:167], v[204:207], v[74:77]
	v_mfma_f32_16x16x32_bf16 v[70:73], v[172:175], v[204:207], v[70:73]
	s_setprio 0
	s_barrier
; #define PG8_STAGE(bufoff, gbase, voff) do { _Pragma("unroll") for (int _i = 0; _i < 2; ++_i) \
;         __builtin_amdgcn_global_load_lds((const unsigned*)((const char*)(gbase) + (voff)[_i]), (PG8_LAS unsigned*)(lds + (bufoff) + ldsw + _i * 8192), 16, 0, 0); } while (0)
; #define PG8_LDA(dst, b, h) do { _Pragma("unroll") for (int m = 0; m < 4; ++m) _Pragma("unroll") for (int k = 0; k < 2; ++k) dst[m][k] = *(const PG8_LAS bf16x8*)(lds + PG8_SA(b, h) + aoff + m * 2048 + k * 1024); } while (0)
; #define PG8_MMA(ai, bj, At, Bt) do { __builtin_amdgcn_s_setprio(1); _Pragma("unroll") for (int m = 0; m < 4; ++m) _Pragma("unroll") for (int n = 0; n < 2; ++n) _Pragma("unroll") for (int k = 0; k < 2; ++k) \
;         acc[ai][bj][m][n] = __builtin_amdgcn_mfma_f32_16x16x32_bf16(Bt[n][k], At[m][k], acc[ai][bj][m][n], 0, 0, 0); __builtin_amdgcn_s_setprio(0); } while (0)
; #define PG8_WAIT_V(n) asm volatile("s_waitcnt vmcnt(" #n ")" ::: "memory")
; #define PG8_WAIT_L(n) asm volatile("s_waitcnt lgkmcnt(" #n ")" ::: "memory")
; #define PG8_BAR __builtin_amdgcn_s_barrier()
; #define PG8_SCHED __builtin_amdgcn_sched_barrier(0)
; template <class Epi, class Sched, bool ALIGN_EPI = false, bool SP2 = false>
; __device__ __forceinline__ void gemm_phase(PG8_LAS unsigned char* lds, const Gemm g, const Sched& S, const Epi& E) {
;     ...
;             PG8_LDA(At, 1, 1); PG8_STAGE(PG8_SB(1, 0), b3, voffB); PG8_STAGE(PG8_SB(1, 1), b3 + hstep, voffB); PG8_STAGE(PG8_SA(1, 0), a3, voffA);
;             PG8_WAIT_V(8); PG8_WAIT_L(0); PG8_BAR; PG8_MMA(1, 0, At, B0); PG8_MMA(1, 1, At, B1); PG8_BAR; PG8_SCHED;
	s_add_i32 s4, s39, s64
	v_lshl_add_u64 v[208:209], v[208:209], 0, s[48:49]
	s_mov_b32 m0, s4
	ds_read_b128 v[176:179], v17 offset:49152
	ds_read_b128 v[180:183], v17 offset:50176
	ds_read_b128 v[184:187], v17 offset:51200
	ds_read_b128 v[188:191], v17 offset:52224
	ds_read_b128 v[192:195], v17 offset:53248
	ds_read_b128 v[196:199], v17 offset:54272
	ds_read_b128 v[200:203], v17 offset:55296
	ds_read_b128 v[204:207], v17 offset:56320
	global_load_lds_dwordx4 v[208:209], off
	v_lshl_add_u64 v[208:209], v[214:215], 0, s[48:49]
	s_add_i32 m0, s4, 0x2000
	s_add_i32 s4, s96, s64
	global_load_lds_dwordx4 v[208:209], off
	v_lshl_add_u64 v[208:209], v[216:217], 0, s[48:49]
	s_mov_b32 m0, s4
	s_nop 0
	global_load_lds_dwordx4 v[208:209], off
	v_lshl_add_u64 v[208:209], v[220:221], 0, s[48:49]
	s_add_i32 m0, s4, 0x2000
	s_nop 0
	global_load_lds_dwordx4 v[208:209], off
	v_lshl_add_u64 v[208:209], v[222:223], 0, s[48:49]
	s_mov_b32 m0, s88
	s_nop 0
	global_load_lds_dwordx4 v[208:209], off
	v_lshl_add_u64 v[208:209], v[232:233], 0, s[48:49]
	s_mov_b32 m0, s89
	s_nop 0
	global_load_lds_dwordx4 v[208:209], off
	s_waitcnt vmcnt(8)
	s_waitcnt lgkmcnt(0)
	s_barrier
	s_setprio 1
	s_waitcnt lgkmcnt(0)
	v_mfma_f32_16x16x32_bf16 v[66:69], v[144:147], v[176:179], v[66:69]
	v_mfma_f32_16x16x32_bf16 v[62:65], v[152:155], v[176:179], v[62:65]
	v_mfma_f32_16x16x32_bf16 v[58:61], v[144:147], v[184:187], v[58:61]
	v_mfma_f32_16x16x32_bf16 v[50:53], v[152:155], v[184:187], v[50:53]
	v_mfma_f32_16x16x32_bf16 v[42:45], v[144:147], v[192:195], v[42:45]
	v_mfma_f32_16x16x32_bf16 v[34:37], v[152:155], v[192:195], v[34:37]
	v_mfma_f32_16x16x32_bf16 v[26:29], v[144:147], v[200:203], v[26:29]
	v_mfma_f32_16x16x32_bf16 v[18:21], v[152:155], v[200:203], v[18:21]
	v_mfma_f32_16x16x32_bf16 v[66:69], v[148:151], v[180:183], v[66:69]
	v_mfma_f32_16x16x32_bf16 v[62:65], v[156:159], v[180:183], v[62:65]
	v_mfma_f32_16x16x32_bf16 v[58:61], v[148:151], v[188:191], v[58:61]
	v_mfma_f32_16x16x32_bf16 v[50:53], v[156:159], v[188:191], v[50:53]
	v_mfma_f32_16x16x32_bf16 v[42:45], v[148:151], v[196:199], v[42:45]
	v_mfma_f32_16x16x32_bf16 v[34:37], v[156:159], v[196:199], v[34:37]
	v_mfma_f32_16x16x32_bf16 v[26:29], v[148:151], v[204:207], v[26:29]
	v_mfma_f32_16x16x32_bf16 v[18:21], v[156:159], v[204:207], v[18:21]
	s_setprio 0
	s_setprio 1
	v_mfma_f32_16x16x32_bf16 v[54:57], v[160:163], v[176:179], v[54:57]
	v_mfma_f32_16x16x32_bf16 v[46:49], v[168:171], v[176:179], v[46:49]
	v_mfma_f32_16x16x32_bf16 v[38:41], v[160:163], v[184:187], v[38:41]
	v_mfma_f32_16x16x32_bf16 v[30:33], v[168:171], v[184:187], v[30:33]
	v_mfma_f32_16x16x32_bf16 v[22:25], v[160:163], v[192:195], v[22:25]
	v_mfma_f32_16x16x32_bf16 v[10:13], v[168:171], v[192:195], v[10:13]
	v_mfma_f32_16x16x32_bf16 v[6:9], v[160:163], v[200:203], v[6:9]
	v_mfma_f32_16x16x32_bf16 v[2:5], v[168:171], v[200:203], v[2:5]
	v_mfma_f32_16x16x32_bf16 v[54:57], v[164:167], v[180:183], v[54:57]
	v_mfma_f32_16x16x32_bf16 v[46:49], v[172:175], v[180:183], v[46:49]
	v_mfma_f32_16x16x32_bf16 v[38:41], v[164:167], v[188:191], v[38:41]
	v_mfma_f32_16x16x32_bf16 v[30:33], v[172:175], v[188:191], v[30:33]
	v_mfma_f32_16x16x32_bf16 v[22:25], v[164:167], v[196:199], v[22:25]
	v_mfma_f32_16x16x32_bf16 v[10:13], v[172:175], v[196:199], v[10:13]
	v_mfma_f32_16x16x32_bf16 v[6:9], v[164:167], v[204:207], v[6:9]
	v_mfma_f32_16x16x32_bf16 v[2:5], v[172:175], v[204:207], v[2:5]
	s_setprio 0
	s_barrier
	s_add_u32 s94, s94, 0x100
	s_addc_u32 s95, s95, 0
	s_add_u32 s36, s36, 0x100
	s_addc_u32 s37, s37, 0
	s_cmp_ge_u32 s38, s77
	s_mov_b32 s4, s38
	s_cbranch_scc0 .LBB0_380
	s_branch .Lgemm_exit_c

; #define PG8_STAGE(bufoff, gbase, voff) do { _Pragma("unroll") for (int _i = 0; _i < 2; ++_i) \
;         __builtin_amdgcn_global_load_lds((const unsigned*)((const char*)(gbase) + (voff)[_i]), (PG8_LAS unsigned*)(lds + (bufoff) + ldsw + _i * 8192), 16, 0, 0); } while (0)
; #define PG8_LDA(dst, b, h) do { _Pragma("unroll") for (int m = 0; m < 4; ++m) _Pragma("unroll") for (int k = 0; k < 2; ++k) dst[m][k] = *(const PG8_LAS bf16x8*)(lds + PG8_SA(b, h) + aoff + m * 2048 + k * 1024); } while (0)
; #define PG8_LDB(dst, b, h) do { _Pragma("unroll") for (int n = 0; n < 2; ++n) _Pragma("unroll") for (int k = 0; k < 2; ++k) dst[n][k] = *(const PG8_LAS bf16x8*)(lds + PG8_SB(b, h) + boff + n * 2048 + k * 1024); } while (0)
; #define PG8_WAIT_V(n) asm volatile("s_waitcnt vmcnt(" #n ")" ::: "memory")
; #define PG8_WAIT_L(n) asm volatile("s_waitcnt lgkmcnt(" #n ")" ::: "memory")
; #define PG8_BAR __builtin_amdgcn_s_barrier()
; template <class Epi, class Sched, bool ALIGN_EPI = false, bool SP2 = false>
; __device__ __forceinline__ void gemm_phase(PG8_LAS unsigned char* lds, const Gemm g, const Sched& S, const Epi& E) {
;     ...
;     f32x4 acc[2][2][4][2];
; #pragma unroll
;     for (int a = 0; a < 2; ++a)
; #pragma unroll
;         for (int b = 0; b < 2; ++b)
; #pragma unroll
;             for (int m = 0; m < 4; ++m)
; #pragma unroll
;                 for (int n = 0; n < 2; ++n) acc[a][b][m][n] = (f32x4){0.f, 0.f, 0.f, 0.f};
;     ...
;         for (int t = 0; t < nt; t += 2) {
;             const bool last = (t == nt - 2);
;             const char* a1 = cA + (size_t)(t + 1) * kstep;
;             const char* a2 = last ? nA : cA + (size_t)(t + 2) * kstep; const char* b2 = last ? nB : cB + (size_t)(t + 2) * kstep;
;             const char* a3 = a2 + kstep; const char* b3 = b2 + kstep;
;             if (last && has_next) S.a_ready(nxt);
;             if constexpr (SP2) {
;             PG8_LDB(B0, 0, 0); PG8_LDB(B1, 0, 1); PG8_SCHED; PG8_LDA(At, 0, 0); PG8_STAGE(PG8_SA(1, 1), a1 + hstep, voffA);
;             PG8_WAIT_V(8); PG8_WAIT_L(0); PG8_BAR; PG8_MMA(0, 0, At, B0); PG8_MMA(0, 1, At, B1); PG8_BAR; PG8_SCHED;
;             PG8_LDA(At, 0, 1); PG8_STAGE(PG8_SB(0, 0), b2, voffB); PG8_STAGE(PG8_SB(0, 1), b2 + hstep, voffB); PG8_STAGE(PG8_SA(0, 0), a2, voffA);
;             PG8_WAIT_V(8); PG8_WAIT_L(0); PG8_BAR; PG8_MMA(1, 0, At, B0); PG8_MMA(1, 1, At, B1); PG8_BAR; PG8_SCHED;
.LBB0_401:
	s_add_u32 s31, s4, 0x100
	s_addc_u32 s41, s5, 0
	s_mov_b32 s43, -2
	s_add_u32 s36, s18, 0x100
	s_addc_u32 s37, s19, 0
	s_add_i32 s47, 0, 0x10000
	s_cmp_eq_u32 s43, 28
	s_cselect_b32 s39, s9, s37
	s_cselect_b32 s38, s8, s36
	s_cselect_b32 s5, s17, s41
	s_cselect_b32 s4, s16, s31
	s_add_i32 s92, 0, 0x14000
	v_add_u32_e32 v156, s47, v1
	v_add_u32_e32 v172, s92, v1
	ds_read_b128 v[144:147], v156
	ds_read_b128 v[148:151], v156 offset:1024
	ds_read_b128 v[152:155], v156 offset:2048
	ds_read_b128 v[156:159], v156 offset:3072
	ds_read_b128 v[160:163], v172
	ds_read_b128 v[164:167], v172 offset:1024
	ds_read_b128 v[168:171], v172 offset:2048
	ds_read_b128 v[172:175], v172 offset:3072
	s_add_i32 m0, s54, 0xc000
	ds_read_b128 v[176:179], v17
	ds_read_b128 v[180:183], v17 offset:1024
	ds_read_b128 v[184:187], v17 offset:2048
	ds_read_b128 v[188:191], v17 offset:3072
	ds_read_b128 v[192:195], v17 offset:4096
	ds_read_b128 v[196:199], v17 offset:5120
	ds_read_b128 v[200:203], v17 offset:6144
	ds_read_b128 v[204:207], v17 offset:7168
	global_load_lds_dwordx4 v142, s[18:19]
	s_add_i32 m0, s54, 0xe000
	s_nop 0
	global_load_lds_dwordx4 v140, s[18:19]
	s_waitcnt vmcnt(8)
	s_waitcnt lgkmcnt(0)
	s_barrier
	s_setprio 1
	s_waitcnt lgkmcnt(0)
	v_mfma_f32_16x16x32_bf16 v[130:133], v[144:147], v[176:179], 0
	v_mfma_f32_16x16x32_bf16 v[122:125], v[152:155], v[176:179], 0
	v_mfma_f32_16x16x32_bf16 v[114:117], v[144:147], v[184:187], 0
	v_mfma_f32_16x16x32_bf16 v[106:109], v[152:155], v[184:187], 0
	v_mfma_f32_16x16x32_bf16 v[98:101], v[144:147], v[192:195], 0
	v_mfma_f32_16x16x32_bf16 v[90:93], v[152:155], v[192:195], 0
	v_mfma_f32_16x16x32_bf16 v[82:85], v[144:147], v[200:203], 0
	v_mfma_f32_16x16x32_bf16 v[74:77], v[152:155], v[200:203], 0
	v_mfma_f32_16x16x32_bf16 v[130:133], v[148:151], v[180:183], v[130:133]
	v_mfma_f32_16x16x32_bf16 v[122:125], v[156:159], v[180:183], v[122:125]
	v_mfma_f32_16x16x32_bf16 v[114:117], v[148:151], v[188:191], v[114:117]
	v_mfma_f32_16x16x32_bf16 v[106:109], v[156:159], v[188:191], v[106:109]
	v_mfma_f32_16x16x32_bf16 v[98:101], v[148:151], v[196:199], v[98:101]
	v_mfma_f32_16x16x32_bf16 v[90:93], v[156:159], v[196:199], v[90:93]
	v_mfma_f32_16x16x32_bf16 v[82:85], v[148:151], v[204:207], v[82:85]
	v_mfma_f32_16x16x32_bf16 v[74:77], v[156:159], v[204:207], v[74:77]
	s_setprio 0
	s_setprio 1
	v_mfma_f32_16x16x32_bf16 v[126:129], v[160:163], v[176:179], 0
	v_mfma_f32_16x16x32_bf16 v[118:121], v[168:171], v[176:179], 0
	v_mfma_f32_16x16x32_bf16 v[110:113], v[160:163], v[184:187], 0
	v_mfma_f32_16x16x32_bf16 v[102:105], v[168:171], v[184:187], 0
	v_mfma_f32_16x16x32_bf16 v[94:97], v[160:163], v[192:195], 0
	v_mfma_f32_16x16x32_bf16 v[86:89], v[168:171], v[192:195], 0
	v_mfma_f32_16x16x32_bf16 v[78:81], v[160:163], v[200:203], 0
	v_mfma_f32_16x16x32_bf16 v[70:73], v[168:171], v[200:203], 0
	v_mfma_f32_16x16x32_bf16 v[126:129], v[164:167], v[180:183], v[126:129]
	v_mfma_f32_16x16x32_bf16 v[118:121], v[172:175], v[180:183], v[118:121]
	v_mfma_f32_16x16x32_bf16 v[110:113], v[164:167], v[188:191], v[110:113]
	v_mfma_f32_16x16x32_bf16 v[102:105], v[172:175], v[188:191], v[102:105]
	v_mfma_f32_16x16x32_bf16 v[94:97], v[164:167], v[196:199], v[94:97]
	v_mfma_f32_16x16x32_bf16 v[86:89], v[172:175], v[196:199], v[86:89]
	v_mfma_f32_16x16x32_bf16 v[78:81], v[164:167], v[204:207], v[78:81]
	v_mfma_f32_16x16x32_bf16 v[70:73], v[172:175], v[204:207], v[70:73]
	s_setprio 0
	s_barrier
	s_add_i32 s18, s47, s46
	s_mov_b32 m0, s18
	ds_read_b128 v[176:179], v17 offset:16384
	ds_read_b128 v[180:183], v17 offset:17408
	ds_read_b128 v[184:187], v17 offset:18432
	ds_read_b128 v[188:191], v17 offset:19456
	ds_read_b128 v[192:195], v17 offset:20480
	ds_read_b128 v[196:199], v17 offset:21504
	ds_read_b128 v[200:203], v17 offset:22528
	ds_read_b128 v[204:207], v17 offset:23552
	global_load_lds_dwordx4 v136, s[4:5]
	s_add_i32 m0, s18, 0x2000
	s_add_u32 s18, s4, 0x84000
	s_addc_u32 s19, s5, 0
	s_add_i32 s47, s92, s46
	global_load_lds_dwordx4 v14, s[4:5]
	s_mov_b32 m0, s47
	s_nop 0
	global_load_lds_dwordx4 v136, s[18:19]
	s_add_i32 m0, s47, 0x2000
	s_nop 0
	global_load_lds_dwordx4 v14, s[18:19]
	s_mov_b32 m0, s54
	s_nop 0
	global_load_lds_dwordx4 v138, s[38:39]
	s_mov_b32 m0, s64
	s_nop 0
	global_load_lds_dwordx4 v134, s[38:39]
	s_waitcnt vmcnt(8)
	s_waitcnt lgkmcnt(0)
	s_barrier
	s_setprio 1
	s_waitcnt lgkmcnt(0)
	v_mfma_f32_16x16x32_bf16 v[66:69], v[144:147], v[176:179], 0
	v_mfma_f32_16x16x32_bf16 v[58:61], v[152:155], v[176:179], 0
	v_mfma_f32_16x16x32_bf16 v[50:53], v[144:147], v[184:187], 0
	v_mfma_f32_16x16x32_bf16 v[42:45], v[152:155], v[184:187], 0
	v_mfma_f32_16x16x32_bf16 v[34:37], v[144:147], v[192:195], 0
	v_mfma_f32_16x16x32_bf16 v[26:29], v[152:155], v[192:195], 0
	v_mfma_f32_16x16x32_bf16 v[18:21], v[144:147], v[200:203], 0
	v_mfma_f32_16x16x32_bf16 v[6:9], v[152:155], v[200:203], 0
	v_mfma_f32_16x16x32_bf16 v[66:69], v[148:151], v[180:183], v[66:69]
	v_mfma_f32_16x16x32_bf16 v[58:61], v[156:159], v[180:183], v[58:61]
	v_mfma_f32_16x16x32_bf16 v[50:53], v[148:151], v[188:191], v[50:53]
	v_mfma_f32_16x16x32_bf16 v[42:45], v[156:159], v[188:191], v[42:45]
	v_mfma_f32_16x16x32_bf16 v[34:37], v[148:151], v[196:199], v[34:37]
	v_mfma_f32_16x16x32_bf16 v[26:29], v[156:159], v[196:199], v[26:29]
	v_mfma_f32_16x16x32_bf16 v[18:21], v[148:151], v[204:207], v[18:21]
	v_mfma_f32_16x16x32_bf16 v[6:9], v[156:159], v[204:207], v[6:9]
	s_setprio 0
	s_setprio 1
	v_mfma_f32_16x16x32_bf16 v[62:65], v[160:163], v[176:179], 0
	v_mfma_f32_16x16x32_bf16 v[54:57], v[168:171], v[176:179], 0
	v_mfma_f32_16x16x32_bf16 v[46:49], v[160:163], v[184:187], 0
	v_mfma_f32_16x16x32_bf16 v[38:41], v[168:171], v[184:187], 0
	v_mfma_f32_16x16x32_bf16 v[30:33], v[160:163], v[192:195], 0
	v_mfma_f32_16x16x32_bf16 v[22:25], v[168:171], v[192:195], 0
	v_mfma_f32_16x16x32_bf16 v[10:13], v[160:163], v[200:203], 0
	v_mfma_f32_16x16x32_bf16 v[2:5], v[168:171], v[200:203], 0
	v_mfma_f32_16x16x32_bf16 v[62:65], v[164:167], v[180:183], v[62:65]
	v_mfma_f32_16x16x32_bf16 v[54:57], v[172:175], v[180:183], v[54:57]
	v_mfma_f32_16x16x32_bf16 v[46:49], v[164:167], v[188:191], v[46:49]
	v_mfma_f32_16x16x32_bf16 v[38:41], v[172:175], v[188:191], v[38:41]
	v_mfma_f32_16x16x32_bf16 v[30:33], v[164:167], v[196:199], v[30:33]
	v_mfma_f32_16x16x32_bf16 v[22:25], v[172:175], v[196:199], v[22:25]
	v_mfma_f32_16x16x32_bf16 v[10:13], v[164:167], v[204:207], v[10:13]
	v_mfma_f32_16x16x32_bf16 v[2:5], v[172:175], v[204:207], v[2:5]
	s_setprio 0
	s_barrier
; #define PG8_STAGE(bufoff, gbase, voff) do { _Pragma("unroll") for (int _i = 0; _i < 2; ++_i) \
;         __builtin_amdgcn_global_load_lds((const unsigned*)((const char*)(gbase) + (voff)[_i]), (PG8_LAS unsigned*)(lds + (bufoff) + ldsw + _i * 8192), 16, 0, 0); } while (0)
; #define PG8_LDA(dst, b, h) do { _Pragma("unroll") for (int m = 0; m < 4; ++m) _Pragma("unroll") for (int k = 0; k < 2; ++k) dst[m][k] = *(const PG8_LAS bf16x8*)(lds + PG8_SA(b, h) + aoff + m * 2048 + k * 1024); } while (0)
; #define PG8_LDB(dst, b, h) do { _Pragma("unroll") for (int n = 0; n < 2; ++n) _Pragma("unroll") for (int k = 0; k < 2; ++k) dst[n][k] = *(const PG8_LAS bf16x8*)(lds + PG8_SB(b, h) + boff + n * 2048 + k * 1024); } while (0)
; #define PG8_MMA(ai, bj, At, Bt) do { __builtin_amdgcn_s_setprio(1); _Pragma("unroll") for (int m = 0; m < 4; ++m) _Pragma("unroll") for (int n = 0; n < 2; ++n) _Pragma("unroll") for (int k = 0; k < 2; ++k) \
;         acc[ai][bj][m][n] = __builtin_amdgcn_mfma_f32_16x16x32_bf16(Bt[n][k], At[m][k], acc[ai][bj][m][n], 0, 0, 0); __builtin_amdgcn_s_setprio(0); } while (0)
; #define PG8_WAIT_V(n) asm volatile("s_waitcnt vmcnt(" #n ")" ::: "memory")
; #define PG8_WAIT_L(n) asm volatile("s_waitcnt lgkmcnt(" #n ")" ::: "memory")
; #define PG8_BAR __builtin_amdgcn_s_barrier()
; #define PG8_SCHED __builtin_amdgcn_sched_barrier(0)
; template <class Epi, class Sched, bool ALIGN_EPI = false, bool SP2 = false>
; __device__ __forceinline__ void gemm_phase(PG8_LAS unsigned char* lds, const Gemm g, const Sched& S, const Epi& E) {
;     ...
;         for (int t = 0; t < nt; t += 2) {
;             const bool last = (t == nt - 2);
;             const char* a1 = cA + (size_t)(t + 1) * kstep;
;             const char* a2 = last ? nA : cA + (size_t)(t + 2) * kstep; const char* b2 = last ? nB : cB + (size_t)(t + 2) * kstep;
;     ...
;             PG8_LDB(B0, 1, 0); PG8_LDB(B1, 1, 1); PG8_SCHED; PG8_LDA(At, 1, 0); PG8_STAGE(PG8_SA(0, 1), a2 + hstep, voffA);
;             PG8_WAIT_V(8); PG8_WAIT_L(0); PG8_BAR; PG8_MMA(0, 0, At, B0); PG8_MMA(0, 1, At, B1); PG8_BAR; PG8_SCHED;
;             PG8_LDA(At, 1, 1); PG8_STAGE(PG8_SB(1, 0), b3, voffB); PG8_STAGE(PG8_SB(1, 1), b3 + hstep, voffB); PG8_STAGE(PG8_SA(1, 0), a3, voffA);
;             PG8_WAIT_V(8); PG8_WAIT_L(0); PG8_BAR; PG8_MMA(1, 0, At, B0); PG8_MMA(1, 1, At, B1); PG8_BAR; PG8_SCHED;
	s_add_i32 s47, 0, 0x18000
	s_add_i32 s92, 0, 0x1c000
	v_add_u32_e32 v156, s47, v1
	v_add_u32_e32 v172, s92, v1
	ds_read_b128 v[144:147], v156
	ds_read_b128 v[148:151], v156 offset:1024
	ds_read_b128 v[152:155], v156 offset:2048
	ds_read_b128 v[156:159], v156 offset:3072
	ds_read_b128 v[160:163], v172
	ds_read_b128 v[164:167], v172 offset:1024
	ds_read_b128 v[168:171], v172 offset:2048
	ds_read_b128 v[172:175], v172 offset:3072
	s_add_u32 s18, s38, 0x84000
	s_addc_u32 s19, s39, 0
	s_mov_b32 m0, s65
	ds_read_b128 v[176:179], v17 offset:32768
	ds_read_b128 v[180:183], v17 offset:33792
	ds_read_b128 v[184:187], v17 offset:34816
	ds_read_b128 v[188:191], v17 offset:35840
	ds_read_b128 v[192:195], v17 offset:36864
	ds_read_b128 v[196:199], v17 offset:37888
	ds_read_b128 v[200:203], v17 offset:38912
	ds_read_b128 v[204:207], v17 offset:39936
	global_load_lds_dwordx4 v138, s[18:19]
	s_mov_b32 m0, s68
	s_nop 0
	global_load_lds_dwordx4 v134, s[18:19]
	s_waitcnt vmcnt(8)
	s_waitcnt lgkmcnt(0)
	s_barrier
	s_setprio 1
	s_waitcnt lgkmcnt(0)
	v_mfma_f32_16x16x32_bf16 v[130:133], v[144:147], v[176:179], v[130:133]
	v_mfma_f32_16x16x32_bf16 v[122:125], v[152:155], v[176:179], v[122:125]
	v_mfma_f32_16x16x32_bf16 v[114:117], v[144:147], v[184:187], v[114:117]
	v_mfma_f32_16x16x32_bf16 v[106:109], v[152:155], v[184:187], v[106:109]
	v_mfma_f32_16x16x32_bf16 v[98:101], v[144:147], v[192:195], v[98:101]
	v_mfma_f32_16x16x32_bf16 v[90:93], v[152:155], v[192:195], v[90:93]
	v_mfma_f32_16x16x32_bf16 v[82:85], v[144:147], v[200:203], v[82:85]
	v_mfma_f32_16x16x32_bf16 v[74:77], v[152:155], v[200:203], v[74:77]
	v_mfma_f32_16x16x32_bf16 v[130:133], v[148:151], v[180:183], v[130:133]
	v_mfma_f32_16x16x32_bf16 v[122:125], v[156:159], v[180:183], v[122:125]
	v_mfma_f32_16x16x32_bf16 v[114:117], v[148:151], v[188:191], v[114:117]
	v_mfma_f32_16x16x32_bf16 v[106:109], v[156:159], v[188:191], v[106:109]
	v_mfma_f32_16x16x32_bf16 v[98:101], v[148:151], v[196:199], v[98:101]
	v_mfma_f32_16x16x32_bf16 v[90:93], v[156:159], v[196:199], v[90:93]
	v_mfma_f32_16x16x32_bf16 v[82:85], v[148:151], v[204:207], v[82:85]
	v_mfma_f32_16x16x32_bf16 v[74:77], v[156:159], v[204:207], v[74:77]
	s_setprio 0
	s_setprio 1
	v_mfma_f32_16x16x32_bf16 v[126:129], v[160:163], v[176:179], v[126:129]
	v_mfma_f32_16x16x32_bf16 v[118:121], v[168:171], v[176:179], v[118:121]
	v_mfma_f32_16x16x32_bf16 v[110:113], v[160:163], v[184:187], v[110:113]
	v_mfma_f32_16x16x32_bf16 v[102:105], v[168:171], v[184:187], v[102:105]
	v_mfma_f32_16x16x32_bf16 v[94:97], v[160:163], v[192:195], v[94:97]
	v_mfma_f32_16x16x32_bf16 v[86:89], v[168:171], v[192:195], v[86:89]
	v_mfma_f32_16x16x32_bf16 v[78:81], v[160:163], v[200:203], v[78:81]
	v_mfma_f32_16x16x32_bf16 v[70:73], v[168:171], v[200:203], v[70:73]
	v_mfma_f32_16x16x32_bf16 v[126:129], v[164:167], v[180:183], v[126:129]
	v_mfma_f32_16x16x32_bf16 v[118:121], v[172:175], v[180:183], v[118:121]
	v_mfma_f32_16x16x32_bf16 v[110:113], v[164:167], v[188:191], v[110:113]
	v_mfma_f32_16x16x32_bf16 v[102:105], v[172:175], v[188:191], v[102:105]
	v_mfma_f32_16x16x32_bf16 v[94:97], v[164:167], v[196:199], v[94:97]
	v_mfma_f32_16x16x32_bf16 v[86:89], v[172:175], v[196:199], v[86:89]
	v_mfma_f32_16x16x32_bf16 v[78:81], v[164:167], v[204:207], v[78:81]
	v_mfma_f32_16x16x32_bf16 v[70:73], v[172:175], v[204:207], v[70:73]
	s_setprio 0
	s_barrier
	s_add_i32 s18, s47, s46
	s_add_u32 s4, s4, 0x80
	s_addc_u32 s5, s5, 0
	s_mov_b32 m0, s18
	ds_read_b128 v[176:179], v17 offset:49152
	ds_read_b128 v[180:183], v17 offset:50176
	ds_read_b128 v[184:187], v17 offset:51200
	ds_read_b128 v[188:191], v17 offset:52224
	ds_read_b128 v[192:195], v17 offset:53248
	ds_read_b128 v[196:199], v17 offset:54272
	ds_read_b128 v[200:203], v17 offset:55296
	ds_read_b128 v[204:207], v17 offset:56320
	global_load_lds_dwordx4 v136, s[4:5]
	s_add_i32 m0, s18, 0x2000
	s_add_i32 s18, s92, s46
	global_load_lds_dwordx4 v14, s[4:5]
	s_add_u32 s4, s4, 0x84000
	s_addc_u32 s5, s5, 0
	s_mov_b32 m0, s18
	s_nop 0
	global_load_lds_dwordx4 v136, s[4:5]
	s_add_i32 m0, s18, 0x2000
	s_nop 0
	global_load_lds_dwordx4 v14, s[4:5]
	s_add_i32 m0, s54, 0x7f80
	s_nop 0
	global_load_lds_dwordx4 v138, s[38:39] offset:128
	s_add_i32 m0, s54, 0x9f80
	s_nop 0
	global_load_lds_dwordx4 v134, s[38:39] offset:128
	s_waitcnt vmcnt(8)
	s_waitcnt lgkmcnt(0)
	s_barrier
	s_setprio 1
	s_waitcnt lgkmcnt(0)
	v_mfma_f32_16x16x32_bf16 v[66:69], v[144:147], v[176:179], v[66:69]
	v_mfma_f32_16x16x32_bf16 v[58:61], v[152:155], v[176:179], v[58:61]
	v_mfma_f32_16x16x32_bf16 v[50:53], v[144:147], v[184:187], v[50:53]
	v_mfma_f32_16x16x32_bf16 v[42:45], v[152:155], v[184:187], v[42:45]
	v_mfma_f32_16x16x32_bf16 v[34:37], v[144:147], v[192:195], v[34:37]
	v_mfma_f32_16x16x32_bf16 v[26:29], v[152:155], v[192:195], v[26:29]
	v_mfma_f32_16x16x32_bf16 v[18:21], v[144:147], v[200:203], v[18:21]
	v_mfma_f32_16x16x32_bf16 v[6:9], v[152:155], v[200:203], v[6:9]
	v_mfma_f32_16x16x32_bf16 v[66:69], v[148:151], v[180:183], v[66:69]
	v_mfma_f32_16x16x32_bf16 v[58:61], v[156:159], v[180:183], v[58:61]
	v_mfma_f32_16x16x32_bf16 v[50:53], v[148:151], v[188:191], v[50:53]
	v_mfma_f32_16x16x32_bf16 v[42:45], v[156:159], v[188:191], v[42:45]
	v_mfma_f32_16x16x32_bf16 v[34:37], v[148:151], v[196:199], v[34:37]
	v_mfma_f32_16x16x32_bf16 v[26:29], v[156:159], v[196:199], v[26:29]
	v_mfma_f32_16x16x32_bf16 v[18:21], v[148:151], v[204:207], v[18:21]
	v_mfma_f32_16x16x32_bf16 v[6:9], v[156:159], v[204:207], v[6:9]
	s_setprio 0
	s_setprio 1
	v_mfma_f32_16x16x32_bf16 v[62:65], v[160:163], v[176:179], v[62:65]
	v_mfma_f32_16x16x32_bf16 v[54:57], v[168:171], v[176:179], v[54:57]
	v_mfma_f32_16x16x32_bf16 v[46:49], v[160:163], v[184:187], v[46:49]
	v_mfma_f32_16x16x32_bf16 v[38:41], v[168:171], v[184:187], v[38:41]
	v_mfma_f32_16x16x32_bf16 v[30:33], v[160:163], v[192:195], v[30:33]
	v_mfma_f32_16x16x32_bf16 v[22:25], v[168:171], v[192:195], v[22:25]
	v_mfma_f32_16x16x32_bf16 v[10:13], v[160:163], v[200:203], v[10:13]
	v_mfma_f32_16x16x32_bf16 v[2:5], v[168:171], v[200:203], v[2:5]
	v_mfma_f32_16x16x32_bf16 v[62:65], v[164:167], v[180:183], v[62:65]
	v_mfma_f32_16x16x32_bf16 v[54:57], v[172:175], v[180:183], v[54:57]
	v_mfma_f32_16x16x32_bf16 v[46:49], v[164:167], v[188:191], v[46:49]
	v_mfma_f32_16x16x32_bf16 v[38:41], v[172:175], v[188:191], v[38:41]
	v_mfma_f32_16x16x32_bf16 v[30:33], v[164:167], v[196:199], v[30:33]
	v_mfma_f32_16x16x32_bf16 v[22:25], v[172:175], v[196:199], v[22:25]
	v_mfma_f32_16x16x32_bf16 v[10:13], v[164:167], v[204:207], v[10:13]
	v_mfma_f32_16x16x32_bf16 v[2:5], v[172:175], v[204:207], v[2:5]
	s_setprio 0
	s_barrier
	s_add_i32 s43, s43, 2
	s_add_u32 s31, s31, 0x100
	s_addc_u32 s41, s41, 0
	s_cmp_gt_u32 s43, 29
	s_mov_b64 s[18:19], s[36:37]
	s_cbranch_scc0 .LBB0_402
	s_branch .Lgemm_exit_d

; #define PG8_BAR __builtin_amdgcn_s_barrier()
; template <class Epi, class Sched, bool ALIGN_EPI = false, bool SP2 = false>
; __device__ __forceinline__ void gemm_phase(PG8_LAS unsigned char* lds, const Gemm g, const Sched& S, const Epi& E) {
;     ...
;         if constexpr (ALIGN_EPI) { if (wr == 0) PG8_BAR; }
.Lgemm_exit_d:
	s_and_b64 vcc, exec, s[14:15]
	s_cbranch_vccz .LBB0_405
	s_barrier
